# removed all s_setprio flips inside the six GEMM K-loops
# speedup vs baseline: 1.0145x; 1.0038x over previous
.LBB0_97:
	s_add_u32 s20, s18, 0x100
	s_addc_u32 s21, s19, 0
	s_add_i32 s43, 0, 0x10000
	s_cmp_eq_u32 s42, 40
	s_cselect_b32 s25, s15, s21
	s_cselect_b32 s24, s14, s20
	s_cselect_b32 s23, s17, s41
	s_cselect_b32 s22, s16, s40
	s_add_i32 s57, 0, 0x14000
	v_add_u32_e32 v136, s43, v183
	v_add_u32_e32 v170, s57, v183
	ds_read_b128 v[108:111], v136
	ds_read_b128 v[112:115], v136 offset:1024
	ds_read_b128 v[132:135], v136 offset:2048
	ds_read_b128 v[136:139], v136 offset:3072
	ds_read_b128 v[140:143], v170
	ds_read_b128 v[144:147], v170 offset:1024
	ds_read_b128 v[166:169], v170 offset:2048
	ds_read_b128 v[170:173], v170 offset:3072
	v_lshl_add_u64 v[194:195], s[18:19], 0, v[162:163]
	s_add_i32 m0, s28, 0xc000
	ds_read_b128 v[174:177], v184
	ds_read_b128 v[178:181], v184 offset:1024
	ds_read_b128 v[186:189], v184 offset:2048
	ds_read_b128 v[190:193], v184 offset:3072
	ds_read_b128 v[206:209], v184 offset:4096
	ds_read_b128 v[210:213], v184 offset:5120
	ds_read_b128 v[214:217], v184 offset:6144
	ds_read_b128 v[218:221], v184 offset:7168
	global_load_lds_dwordx4 v[194:195], off
	v_lshl_add_u64 v[194:195], s[18:19], 0, v[164:165]
	s_add_i32 m0, s28, 0xe000
	s_nop 0
	global_load_lds_dwordx4 v[194:195], off
	s_waitcnt vmcnt(8)
	s_waitcnt lgkmcnt(0)
	s_barrier
	s_waitcnt lgkmcnt(0)
	v_mfma_f32_16x16x32_bf16 v[152:155], v[108:111], v[174:177], v[152:155]
	v_mfma_f32_16x16x32_bf16 v[148:151], v[132:135], v[174:177], v[148:151]
	v_mfma_f32_16x16x32_bf16 v[128:131], v[108:111], v[186:189], v[128:131]
	v_mfma_f32_16x16x32_bf16 v[124:127], v[132:135], v[186:189], v[124:127]
	v_mfma_f32_16x16x32_bf16 v[100:103], v[108:111], v[206:209], v[100:103]
	v_mfma_f32_16x16x32_bf16 v[92:95], v[132:135], v[206:209], v[92:95]
	v_mfma_f32_16x16x32_bf16 v[80:83], v[108:111], v[214:217], v[80:83]
	v_mfma_f32_16x16x32_bf16 v[76:79], v[132:135], v[214:217], v[76:79]
	v_mfma_f32_16x16x32_bf16 v[152:155], v[112:115], v[178:181], v[152:155]
	v_mfma_f32_16x16x32_bf16 v[148:151], v[136:139], v[178:181], v[148:151]
	v_mfma_f32_16x16x32_bf16 v[128:131], v[112:115], v[190:193], v[128:131]
	v_mfma_f32_16x16x32_bf16 v[124:127], v[136:139], v[190:193], v[124:127]
	v_mfma_f32_16x16x32_bf16 v[100:103], v[112:115], v[210:213], v[100:103]
	v_mfma_f32_16x16x32_bf16 v[92:95], v[136:139], v[210:213], v[92:95]
	v_mfma_f32_16x16x32_bf16 v[80:83], v[112:115], v[218:221], v[80:83]
	v_mfma_f32_16x16x32_bf16 v[76:79], v[136:139], v[218:221], v[76:79]
	v_mfma_f32_16x16x32_bf16 v[104:107], v[140:143], v[174:177], v[104:107]
	v_mfma_f32_16x16x32_bf16 v[96:99], v[166:169], v[174:177], v[96:99]
	v_mfma_f32_16x16x32_bf16 v[120:123], v[140:143], v[186:189], v[120:123]
	v_mfma_f32_16x16x32_bf16 v[116:119], v[166:169], v[186:189], v[116:119]
	v_mfma_f32_16x16x32_bf16 v[88:91], v[140:143], v[206:209], v[88:91]
	v_mfma_f32_16x16x32_bf16 v[84:87], v[166:169], v[206:209], v[84:87]
	v_mfma_f32_16x16x32_bf16 v[72:75], v[140:143], v[214:217], v[72:75]
	v_mfma_f32_16x16x32_bf16 v[68:71], v[166:169], v[214:217], v[68:71]
	v_mfma_f32_16x16x32_bf16 v[104:107], v[144:147], v[178:181], v[104:107]
	v_mfma_f32_16x16x32_bf16 v[96:99], v[170:173], v[178:181], v[96:99]
	v_mfma_f32_16x16x32_bf16 v[120:123], v[144:147], v[190:193], v[120:123]
	v_mfma_f32_16x16x32_bf16 v[116:119], v[170:173], v[190:193], v[116:119]
	v_mfma_f32_16x16x32_bf16 v[88:91], v[144:147], v[210:213], v[88:91]
	v_mfma_f32_16x16x32_bf16 v[84:87], v[170:173], v[210:213], v[84:87]
	v_mfma_f32_16x16x32_bf16 v[72:75], v[144:147], v[218:221], v[72:75]
	v_mfma_f32_16x16x32_bf16 v[68:71], v[170:173], v[218:221], v[68:71]
	s_barrier
	s_add_i32 s18, s43, s27
	v_lshl_add_u64 v[194:195], s[22:23], 0, v[2:3]
	s_mov_b32 m0, s18
	ds_read_b128 v[174:177], v184 offset:16384
	ds_read_b128 v[178:181], v184 offset:17408
	ds_read_b128 v[186:189], v184 offset:18432
	ds_read_b128 v[190:193], v184 offset:19456
	ds_read_b128 v[206:209], v184 offset:20480
	ds_read_b128 v[210:213], v184 offset:21504
	ds_read_b128 v[214:217], v184 offset:22528
	ds_read_b128 v[218:221], v184 offset:23552
	global_load_lds_dwordx4 v[194:195], off
	s_add_i32 m0, s18, 0x2000
	s_add_u32 s18, s22, 0xb0000
	v_lshl_add_u64 v[236:237], s[22:23], 0, v[156:157]
	s_addc_u32 s19, s23, 0
	s_add_i32 s43, s57, s27
	global_load_lds_dwordx4 v[236:237], off
	v_lshl_add_u64 v[238:239], s[18:19], 0, v[2:3]
	s_mov_b32 m0, s43
	v_lshl_add_u64 v[240:241], s[24:25], 0, v[158:159]
	global_load_lds_dwordx4 v[238:239], off
	v_lshl_add_u64 v[238:239], s[18:19], 0, v[156:157]
	s_add_i32 m0, s43, 0x2000
	s_nop 0
	global_load_lds_dwordx4 v[238:239], off
	v_lshl_add_u64 v[238:239], s[24:25], 0, v[160:161]
	s_mov_b32 m0, s28
	s_nop 0
	global_load_lds_dwordx4 v[238:239], off
	s_mov_b32 m0, s29
	s_nop 0
	global_load_lds_dwordx4 v[240:241], off
	s_waitcnt vmcnt(8)
	s_waitcnt lgkmcnt(0)
	s_barrier
	s_waitcnt lgkmcnt(0)
	v_mfma_f32_16x16x32_bf16 v[64:67], v[108:111], v[174:177], v[64:67]
	v_mfma_f32_16x16x32_bf16 v[60:63], v[132:135], v[174:177], v[60:63]
	v_mfma_f32_16x16x32_bf16 v[48:51], v[108:111], v[186:189], v[48:51]
	v_mfma_f32_16x16x32_bf16 v[44:47], v[132:135], v[186:189], v[44:47]
	v_mfma_f32_16x16x32_bf16 v[32:35], v[108:111], v[206:209], v[32:35]
	v_mfma_f32_16x16x32_bf16 v[28:31], v[132:135], v[206:209], v[28:31]
	v_mfma_f32_16x16x32_bf16 v[16:19], v[108:111], v[214:217], v[16:19]
	v_mfma_f32_16x16x32_bf16 v[12:15], v[132:135], v[214:217], v[12:15]
	v_mfma_f32_16x16x32_bf16 v[64:67], v[112:115], v[178:181], v[64:67]
	v_mfma_f32_16x16x32_bf16 v[60:63], v[136:139], v[178:181], v[60:63]
	v_mfma_f32_16x16x32_bf16 v[48:51], v[112:115], v[190:193], v[48:51]
	v_mfma_f32_16x16x32_bf16 v[44:47], v[136:139], v[190:193], v[44:47]
	v_mfma_f32_16x16x32_bf16 v[32:35], v[112:115], v[210:213], v[32:35]
	v_mfma_f32_16x16x32_bf16 v[28:31], v[136:139], v[210:213], v[28:31]
	v_mfma_f32_16x16x32_bf16 v[16:19], v[112:115], v[218:221], v[16:19]
	v_mfma_f32_16x16x32_bf16 v[12:15], v[136:139], v[218:221], v[12:15]
	v_mfma_f32_16x16x32_bf16 v[56:59], v[140:143], v[174:177], v[56:59]
	v_mfma_f32_16x16x32_bf16 v[52:55], v[166:169], v[174:177], v[52:55]
	v_mfma_f32_16x16x32_bf16 v[40:43], v[140:143], v[186:189], v[40:43]
	v_mfma_f32_16x16x32_bf16 v[36:39], v[166:169], v[186:189], v[36:39]
	v_mfma_f32_16x16x32_bf16 v[24:27], v[140:143], v[206:209], v[24:27]
	v_mfma_f32_16x16x32_bf16 v[20:23], v[166:169], v[206:209], v[20:23]
	v_mfma_f32_16x16x32_bf16 v[8:11], v[140:143], v[214:217], v[8:11]
	v_mfma_f32_16x16x32_bf16 v[4:7], v[166:169], v[214:217], v[4:7]
	v_mfma_f32_16x16x32_bf16 v[56:59], v[144:147], v[178:181], v[56:59]
	v_mfma_f32_16x16x32_bf16 v[52:55], v[170:173], v[178:181], v[52:55]
	v_mfma_f32_16x16x32_bf16 v[40:43], v[144:147], v[190:193], v[40:43]
	v_mfma_f32_16x16x32_bf16 v[36:39], v[170:173], v[190:193], v[36:39]
	v_mfma_f32_16x16x32_bf16 v[24:27], v[144:147], v[210:213], v[24:27]
	v_mfma_f32_16x16x32_bf16 v[20:23], v[170:173], v[210:213], v[20:23]
	v_mfma_f32_16x16x32_bf16 v[8:11], v[144:147], v[218:221], v[8:11]
	v_mfma_f32_16x16x32_bf16 v[4:7], v[170:173], v[218:221], v[4:7]
	s_barrier
	s_add_i32 s43, 0, 0x18000
	s_add_i32 s57, 0, 0x1c000
	v_add_u32_e32 v136, s43, v183
	v_add_u32_e32 v170, s57, v183
	ds_read_b128 v[108:111], v136
	ds_read_b128 v[112:115], v136 offset:1024
	ds_read_b128 v[132:135], v136 offset:2048
	ds_read_b128 v[136:139], v136 offset:3072
	ds_read_b128 v[140:143], v170
	ds_read_b128 v[144:147], v170 offset:1024
	ds_read_b128 v[166:169], v170 offset:2048
	ds_read_b128 v[170:173], v170 offset:3072
	s_add_u32 s18, s24, 0xb0000
	s_addc_u32 s19, s25, 0
	s_mov_b32 m0, s30
	v_lshl_add_u64 v[242:243], s[18:19], 0, v[160:161]
	ds_read_b128 v[174:177], v184 offset:32768
	ds_read_b128 v[178:181], v184 offset:33792
	ds_read_b128 v[186:189], v184 offset:34816
	ds_read_b128 v[190:193], v184 offset:35840
	ds_read_b128 v[206:209], v184 offset:36864
	ds_read_b128 v[210:213], v184 offset:37888
	ds_read_b128 v[214:217], v184 offset:38912
	ds_read_b128 v[218:221], v184 offset:39936
	global_load_lds_dwordx4 v[242:243], off
	v_lshl_add_u64 v[242:243], s[18:19], 0, v[158:159]
	s_mov_b32 m0, s31
	s_nop 0
	global_load_lds_dwordx4 v[242:243], off
	s_waitcnt vmcnt(8)
	s_waitcnt lgkmcnt(0)
	s_barrier
	s_waitcnt lgkmcnt(0)
	v_mfma_f32_16x16x32_bf16 v[152:155], v[108:111], v[174:177], v[152:155]
	v_mfma_f32_16x16x32_bf16 v[148:151], v[132:135], v[174:177], v[148:151]
	v_mfma_f32_16x16x32_bf16 v[128:131], v[108:111], v[186:189], v[128:131]
	v_mfma_f32_16x16x32_bf16 v[124:127], v[132:135], v[186:189], v[124:127]
	v_mfma_f32_16x16x32_bf16 v[100:103], v[108:111], v[206:209], v[100:103]
	v_mfma_f32_16x16x32_bf16 v[92:95], v[132:135], v[206:209], v[92:95]
	v_mfma_f32_16x16x32_bf16 v[80:83], v[108:111], v[214:217], v[80:83]
	v_mfma_f32_16x16x32_bf16 v[76:79], v[132:135], v[214:217], v[76:79]
	v_mfma_f32_16x16x32_bf16 v[152:155], v[112:115], v[178:181], v[152:155]
	v_mfma_f32_16x16x32_bf16 v[148:151], v[136:139], v[178:181], v[148:151]
	v_mfma_f32_16x16x32_bf16 v[128:131], v[112:115], v[190:193], v[128:131]
	v_mfma_f32_16x16x32_bf16 v[124:127], v[136:139], v[190:193], v[124:127]
	v_mfma_f32_16x16x32_bf16 v[100:103], v[112:115], v[210:213], v[100:103]
	v_mfma_f32_16x16x32_bf16 v[92:95], v[136:139], v[210:213], v[92:95]
	v_mfma_f32_16x16x32_bf16 v[80:83], v[112:115], v[218:221], v[80:83]
	v_mfma_f32_16x16x32_bf16 v[76:79], v[136:139], v[218:221], v[76:79]
	v_mfma_f32_16x16x32_bf16 v[104:107], v[140:143], v[174:177], v[104:107]
	v_mfma_f32_16x16x32_bf16 v[96:99], v[166:169], v[174:177], v[96:99]
	v_mfma_f32_16x16x32_bf16 v[120:123], v[140:143], v[186:189], v[120:123]
	v_mfma_f32_16x16x32_bf16 v[116:119], v[166:169], v[186:189], v[116:119]
	v_mfma_f32_16x16x32_bf16 v[88:91], v[140:143], v[206:209], v[88:91]
	v_mfma_f32_16x16x32_bf16 v[84:87], v[166:169], v[206:209], v[84:87]
	v_mfma_f32_16x16x32_bf16 v[72:75], v[140:143], v[214:217], v[72:75]
	v_mfma_f32_16x16x32_bf16 v[68:71], v[166:169], v[214:217], v[68:71]
	v_mfma_f32_16x16x32_bf16 v[104:107], v[144:147], v[178:181], v[104:107]
	v_mfma_f32_16x16x32_bf16 v[96:99], v[170:173], v[178:181], v[96:99]
	v_mfma_f32_16x16x32_bf16 v[120:123], v[144:147], v[190:193], v[120:123]
	v_mfma_f32_16x16x32_bf16 v[116:119], v[170:173], v[190:193], v[116:119]
	v_mfma_f32_16x16x32_bf16 v[88:91], v[144:147], v[210:213], v[88:91]
	v_mfma_f32_16x16x32_bf16 v[84:87], v[170:173], v[210:213], v[84:87]
	v_mfma_f32_16x16x32_bf16 v[72:75], v[144:147], v[218:221], v[72:75]
	v_mfma_f32_16x16x32_bf16 v[68:71], v[170:173], v[218:221], v[68:71]
	s_barrier
	s_add_i32 s18, s43, s27
	v_lshl_add_u64 v[194:195], v[194:195], 0, s[96:97]
	s_mov_b32 m0, s18
	ds_read_b128 v[174:177], v184 offset:49152
	ds_read_b128 v[178:181], v184 offset:50176
	ds_read_b128 v[186:189], v184 offset:51200
	ds_read_b128 v[190:193], v184 offset:52224
	ds_read_b128 v[206:209], v184 offset:53248
	ds_read_b128 v[210:213], v184 offset:54272
	ds_read_b128 v[214:217], v184 offset:55296
	ds_read_b128 v[218:221], v184 offset:56320
	global_load_lds_dwordx4 v[194:195], off
	s_add_i32 m0, s18, 0x2000
	s_add_u32 s18, s22, 0xb0080
	v_lshl_add_u64 v[194:195], v[236:237], 0, s[96:97]
	s_addc_u32 s19, s23, 0
	s_add_i32 s22, s57, s27
	global_load_lds_dwordx4 v[194:195], off
	v_lshl_add_u64 v[194:195], s[18:19], 0, v[2:3]
	s_mov_b32 m0, s22
	s_nop 0
	global_load_lds_dwordx4 v[194:195], off
	v_lshl_add_u64 v[194:195], s[18:19], 0, v[156:157]
	s_add_i32 m0, s22, 0x2000
	s_nop 0
	global_load_lds_dwordx4 v[194:195], off
	v_lshl_add_u64 v[194:195], v[238:239], 0, s[96:97]
	s_mov_b32 m0, s36
	s_nop 0
	global_load_lds_dwordx4 v[194:195], off
	v_lshl_add_u64 v[194:195], v[240:241], 0, s[96:97]
	s_mov_b32 m0, s37
	s_nop 0
	global_load_lds_dwordx4 v[194:195], off
	s_waitcnt vmcnt(8)
	s_waitcnt lgkmcnt(0)
	s_barrier
	s_waitcnt lgkmcnt(0)
	v_mfma_f32_16x16x32_bf16 v[64:67], v[108:111], v[174:177], v[64:67]
	v_mfma_f32_16x16x32_bf16 v[60:63], v[132:135], v[174:177], v[60:63]
	v_mfma_f32_16x16x32_bf16 v[48:51], v[108:111], v[186:189], v[48:51]
	v_mfma_f32_16x16x32_bf16 v[44:47], v[132:135], v[186:189], v[44:47]
	v_mfma_f32_16x16x32_bf16 v[32:35], v[108:111], v[206:209], v[32:35]
	v_mfma_f32_16x16x32_bf16 v[28:31], v[132:135], v[206:209], v[28:31]
	v_mfma_f32_16x16x32_bf16 v[16:19], v[108:111], v[214:217], v[16:19]
	v_mfma_f32_16x16x32_bf16 v[12:15], v[132:135], v[214:217], v[12:15]
	v_mfma_f32_16x16x32_bf16 v[64:67], v[112:115], v[178:181], v[64:67]
	v_mfma_f32_16x16x32_bf16 v[60:63], v[136:139], v[178:181], v[60:63]
	v_mfma_f32_16x16x32_bf16 v[48:51], v[112:115], v[190:193], v[48:51]
	v_mfma_f32_16x16x32_bf16 v[44:47], v[136:139], v[190:193], v[44:47]
	v_mfma_f32_16x16x32_bf16 v[32:35], v[112:115], v[210:213], v[32:35]
	v_mfma_f32_16x16x32_bf16 v[28:31], v[136:139], v[210:213], v[28:31]
	v_mfma_f32_16x16x32_bf16 v[16:19], v[112:115], v[218:221], v[16:19]
	v_mfma_f32_16x16x32_bf16 v[12:15], v[136:139], v[218:221], v[12:15]
	v_mfma_f32_16x16x32_bf16 v[56:59], v[140:143], v[174:177], v[56:59]
	v_mfma_f32_16x16x32_bf16 v[52:55], v[166:169], v[174:177], v[52:55]
	v_mfma_f32_16x16x32_bf16 v[40:43], v[140:143], v[186:189], v[40:43]
	v_mfma_f32_16x16x32_bf16 v[36:39], v[166:169], v[186:189], v[36:39]
	v_mfma_f32_16x16x32_bf16 v[24:27], v[140:143], v[206:209], v[24:27]
	v_mfma_f32_16x16x32_bf16 v[20:23], v[166:169], v[206:209], v[20:23]
	v_mfma_f32_16x16x32_bf16 v[8:11], v[140:143], v[214:217], v[8:11]
	v_mfma_f32_16x16x32_bf16 v[4:7], v[166:169], v[214:217], v[4:7]
	v_mfma_f32_16x16x32_bf16 v[56:59], v[144:147], v[178:181], v[56:59]
	v_mfma_f32_16x16x32_bf16 v[52:55], v[170:173], v[178:181], v[52:55]
	v_mfma_f32_16x16x32_bf16 v[40:43], v[144:147], v[190:193], v[40:43]
	v_mfma_f32_16x16x32_bf16 v[36:39], v[170:173], v[190:193], v[36:39]
	v_mfma_f32_16x16x32_bf16 v[24:27], v[144:147], v[210:213], v[24:27]
	v_mfma_f32_16x16x32_bf16 v[20:23], v[170:173], v[210:213], v[20:23]
	v_mfma_f32_16x16x32_bf16 v[8:11], v[144:147], v[218:221], v[8:11]
	v_mfma_f32_16x16x32_bf16 v[4:7], v[170:173], v[218:221], v[4:7]
	s_barrier
	s_add_i32 s42, s42, 2
	s_add_u32 s40, s40, 0x100
	s_addc_u32 s41, s41, 0
	s_cmp_gt_u32 s42, 41
	s_mov_b64 s[18:19], s[20:21]
	s_cbranch_scc0 .LBB0_97
	v_mov_b32_e32 v109, v182
	v_mov_b32_e32 v169, v1
	s_lshl_b32 s18, s56, 8
	s_lshl_b32 s19, s55, 8
	s_add_i32 s18, s18, s34
	s_or_b32 s19, s19, s35
	v_lshl_add_u32 v170, v169, 4, v109
	v_add_u32_e32 v174, s18, v109
	v_lshl_add_u32 v108, v169, 3, s19
	v_and_b32_e32 v166, 3, v109
	v_and_b32_e32 v109, -4, v170
	v_lshl_add_u32 v185, v166, 6, v109
	v_ashrrev_i32_e32 v109, 31, v108
	v_ashrrev_i32_e32 v175, 31, v174
	v_lshl_add_u64 v[176:177], v[108:109], 1, s[48:49]
	v_lshlrev_b64 v[108:109], 11, v[174:175]
	v_lshl_add_u64 v[108:109], v[176:177], 0, v[108:109]
	global_load_dwordx4 v[188:191], v[108:109], off
	global_load_dwordx4 v[192:195], v[108:109], off offset:256
	v_add_u32_e32 v180, 16, v174
	v_ashrrev_i32_e32 v181, 31, v180
	v_lshlrev_b64 v[108:109], 11, v[180:181]
	v_add_u32_e32 v178, 32, v174
	v_lshl_add_u64 v[108:109], v[176:177], 0, v[108:109]
	v_ashrrev_i32_e32 v179, 31, v178
	global_load_dwordx4 v[144:147], v[108:109], off
	global_load_dwordx4 v[140:143], v[108:109], off offset:256
	v_lshlrev_b64 v[108:109], 11, v[178:179]
	v_add_u32_e32 v172, 48, v174
	v_ashrrev_i32_e32 v167, 2, v170
	v_lshlrev_b32_e32 v170, 2, v170
	v_lshl_add_u64 v[108:109], v[176:177], 0, v[108:109]
	v_ashrrev_i32_e32 v173, 31, v172
	v_xor_b32_e32 v187, 64, v170
	v_xor_b32_e32 v186, 0x80, v170
	v_add_u32_e32 v170, 0x80, v174
	global_load_dwordx4 v[136:139], v[108:109], off
	global_load_dwordx4 v[132:135], v[108:109], off offset:256
	v_lshlrev_b64 v[108:109], 11, v[172:173]
	v_ashrrev_i32_e32 v171, 31, v170
	v_lshl_add_u64 v[108:109], v[176:177], 0, v[108:109]
	global_load_dwordx4 v[112:115], v[108:109], off
	s_nop 0
	global_load_dwordx4 v[108:111], v[108:109], off offset:256
	v_add_u32_e32 v168, s18, v167
	s_lshl_b32 s18, s55, 2
	v_lshl_or_b32 v166, v166, 3, s19
	s_ashr_i32 s19, s18, 31
	v_ashrrev_i32_e32 v167, 31, v166
	v_cmp_eq_u32_e64 s[40:41], 0, v169
	s_lshl_b64 s[18:19], s[18:19], 2
	v_ashrrev_i32_e32 v169, 31, v168
	v_lshl_add_u64 v[166:167], v[166:167], 1, s[48:49]
	s_add_u32 s18, s50, s18
	s_addc_u32 s19, s51, s19
	s_waitcnt vmcnt(0)
	v_lshlrev_b32_e32 v208, 16, v190
	v_and_b32_e32 v209, 0xffff0000, v190
	v_lshlrev_b32_e32 v206, 16, v188
	v_and_b32_e32 v207, 0xffff0000, v188
	v_lshlrev_b32_e32 v188, 16, v189
	v_and_b32_e32 v189, 0xffff0000, v189
	v_lshlrev_b32_e32 v190, 16, v191
	v_and_b32_e32 v191, 0xffff0000, v191
	v_pk_add_f32 v[148:149], v[148:149], v[208:209]
	v_pk_add_f32 v[188:189], v[154:155], v[188:189]
	v_pk_add_f32 v[206:207], v[152:153], v[206:207]
	v_pk_add_f32 v[190:191], v[150:151], v[190:191]
	v_cvt_pk_bf16_f32 v153, v148, v149
	v_mul_f32_e32 v149, v149, v149
	v_mul_f32_e32 v150, v207, v207
	v_mul_f32_e32 v155, v189, v189
	v_fmac_f32_e32 v149, v148, v148
	v_mul_f32_e32 v148, v191, v191
	v_fmac_f32_e32 v150, v206, v206
	v_fmac_f32_e32 v155, v188, v188
	v_fmac_f32_e32 v148, v190, v190
	v_add_f32_e32 v150, v150, v155
	v_add_f32_e32 v148, v149, v148
	v_cvt_pk_bf16_f32 v154, v190, v191
	v_add_f32_e32 v150, v150, v148
	v_lshlrev_b32_e32 v148, 16, v192
	v_and_b32_e32 v149, 0xffff0000, v192
	v_lshlrev_b32_e32 v190, 16, v194
	v_and_b32_e32 v191, 0xffff0000, v194
	v_cvt_pk_bf16_f32 v152, v188, v189
	v_lshlrev_b32_e32 v188, 16, v193
	v_and_b32_e32 v189, 0xffff0000, v193
	v_lshlrev_b32_e32 v192, 16, v195
	v_and_b32_e32 v193, 0xffff0000, v195
	v_pk_add_f32 v[104:105], v[104:105], v[148:149]
	v_pk_add_f32 v[96:97], v[96:97], v[190:191]
	v_pk_add_f32 v[106:107], v[106:107], v[188:189]
	v_pk_add_f32 v[98:99], v[98:99], v[192:193]
	v_cvt_pk_bf16_f32 v155, v104, v105
	v_cvt_pk_bf16_f32 v189, v96, v97
	v_mul_f32_e32 v105, v105, v105
	v_mul_f32_e32 v97, v97, v97
	v_fmac_f32_e32 v105, v104, v104
	v_mul_f32_e32 v104, v107, v107
	v_fmac_f32_e32 v97, v96, v96
	v_mul_f32_e32 v96, v99, v99
	v_fmac_f32_e32 v104, v106, v106
	v_fmac_f32_e32 v96, v98, v98
	v_add_f32_e32 v104, v105, v104
	v_add_f32_e32 v96, v97, v96
	v_add_f32_e32 v96, v104, v96
	v_add_f32_e32 v150, v150, v96
	v_lshlrev_b64 v[96:97], 11, v[170:171]
	v_lshl_add_u64 v[96:97], v[176:177], 0, v[96:97]
	v_cvt_pk_bf16_f32 v188, v106, v107
	v_cvt_pk_bf16_f32 v190, v98, v99
	global_load_dwordx4 v[104:107], v[96:97], off
	s_nop 0
	global_load_dwordx4 v[96:99], v[96:97], off offset:256
	v_cvt_pk_bf16_f32 v151, v206, v207
	ds_bpermute_b32 v192, v185, v151
	ds_bpermute_b32 v151, v187, v150
	ds_bpermute_b32 v193, v185, v152
	ds_bpermute_b32 v194, v185, v153
	ds_bpermute_b32 v195, v185, v154
	ds_bpermute_b32 v152, v185, v155
	s_waitcnt lgkmcnt(4)
	v_add_f32_e32 v150, v150, v151
	ds_bpermute_b32 v153, v185, v188
	ds_bpermute_b32 v154, v185, v189
	ds_bpermute_b32 v155, v185, v190
	ds_bpermute_b32 v151, v186, v150
	v_lshlrev_b64 v[148:149], 11, v[168:169]
	v_lshl_add_u64 v[148:149], v[166:167], 0, v[148:149]
	s_waitcnt lgkmcnt(5)
	global_store_dwordx4 v[148:149], v[192:195], off
	s_waitcnt lgkmcnt(1)
	global_store_dwordx4 v[148:149], v[152:155], off offset:256
	s_and_saveexec_b64 s[20:21], s[40:41]
	s_cbranch_execz .LBB0_100
	s_waitcnt lgkmcnt(0)
	v_add_f32_e32 v152, v150, v151
	v_lshlrev_b64 v[150:151], 6, v[174:175]
	v_lshl_add_u64 v[150:151], s[18:19], 0, v[150:151]
	global_store_dword v[150:151], v152, off

.LBB0_156:
	s_add_u32 s16, s14, 0x100
	s_addc_u32 s17, s15, 0
	s_add_i32 s69, 0, 0x10000
	s_cmp_eq_u32 s68, 40
	s_cselect_b32 s21, s41, s17
	s_cselect_b32 s20, s40, s16
	v_add_u32_e32 v2, s69, v207
	s_cselect_b32 s19, s57, s67
	s_cselect_b32 s18, s56, s66
	s_add_i32 s70, 0, 0x14000
	ds_read_b128 v[108:111], v2
	ds_read_b128 v[112:115], v2 offset:1024
	ds_read_b128 v[132:135], v2 offset:2048
	ds_read_b128 v[136:139], v2 offset:3072
	v_add_u32_e32 v2, s70, v207
	ds_read_b128 v[148:151], v2
	ds_read_b128 v[152:155], v2 offset:1024
	ds_read_b128 v[168:171], v2 offset:2048
	ds_read_b128 v[172:175], v2 offset:3072
	v_lshl_add_u64 v[236:237], s[14:15], 0, v[164:165]
	s_add_i32 m0, s25, 0xc000
	ds_read_b128 v[176:179], v208
	ds_read_b128 v[180:183], v208 offset:1024
	ds_read_b128 v[184:187], v208 offset:2048
	ds_read_b128 v[188:191], v208 offset:3072
	ds_read_b128 v[192:195], v208 offset:4096
	ds_read_b128 v[210:213], v208 offset:5120
	ds_read_b128 v[214:217], v208 offset:6144
	ds_read_b128 v[218:221], v208 offset:7168
	global_load_lds_dwordx4 v[236:237], off
	v_lshl_add_u64 v[236:237], s[14:15], 0, v[166:167]
	s_add_i32 m0, s25, 0xe000
	s_nop 0
	global_load_lds_dwordx4 v[236:237], off
	s_waitcnt vmcnt(8)
	s_waitcnt lgkmcnt(0)
	s_barrier
	s_waitcnt lgkmcnt(0)
	v_mfma_f32_16x16x32_bf16 v[144:147], v[108:111], v[176:179], v[144:147]
	v_mfma_f32_16x16x32_bf16 v[140:143], v[132:135], v[176:179], v[140:143]
	v_mfma_f32_16x16x32_bf16 v[128:131], v[108:111], v[184:187], v[128:131]
	v_mfma_f32_16x16x32_bf16 v[124:127], v[132:135], v[184:187], v[124:127]
	v_mfma_f32_16x16x32_bf16 v[96:99], v[108:111], v[192:195], v[96:99]
	v_mfma_f32_16x16x32_bf16 v[92:95], v[132:135], v[192:195], v[92:95]
	v_mfma_f32_16x16x32_bf16 v[80:83], v[108:111], v[214:217], v[80:83]
	v_mfma_f32_16x16x32_bf16 v[76:79], v[132:135], v[214:217], v[76:79]
	v_mfma_f32_16x16x32_bf16 v[144:147], v[112:115], v[180:183], v[144:147]
	v_mfma_f32_16x16x32_bf16 v[140:143], v[136:139], v[180:183], v[140:143]
	v_mfma_f32_16x16x32_bf16 v[128:131], v[112:115], v[188:191], v[128:131]
	v_mfma_f32_16x16x32_bf16 v[124:127], v[136:139], v[188:191], v[124:127]
	v_mfma_f32_16x16x32_bf16 v[96:99], v[112:115], v[210:213], v[96:99]
	v_mfma_f32_16x16x32_bf16 v[92:95], v[136:139], v[210:213], v[92:95]
	v_mfma_f32_16x16x32_bf16 v[80:83], v[112:115], v[218:221], v[80:83]
	v_mfma_f32_16x16x32_bf16 v[76:79], v[136:139], v[218:221], v[76:79]
	v_mfma_f32_16x16x32_bf16 v[104:107], v[148:151], v[176:179], v[104:107]
	v_mfma_f32_16x16x32_bf16 v[100:103], v[168:171], v[176:179], v[100:103]
	v_mfma_f32_16x16x32_bf16 v[120:123], v[148:151], v[184:187], v[120:123]
	v_mfma_f32_16x16x32_bf16 v[116:119], v[168:171], v[184:187], v[116:119]
	v_mfma_f32_16x16x32_bf16 v[88:91], v[148:151], v[192:195], v[88:91]
	v_mfma_f32_16x16x32_bf16 v[84:87], v[168:171], v[192:195], v[84:87]
	v_mfma_f32_16x16x32_bf16 v[72:75], v[148:151], v[214:217], v[72:75]
	v_mfma_f32_16x16x32_bf16 v[68:71], v[168:171], v[214:217], v[68:71]
	v_mfma_f32_16x16x32_bf16 v[104:107], v[152:155], v[180:183], v[104:107]
	v_mfma_f32_16x16x32_bf16 v[100:103], v[172:175], v[180:183], v[100:103]
	v_mfma_f32_16x16x32_bf16 v[120:123], v[152:155], v[188:191], v[120:123]
	v_mfma_f32_16x16x32_bf16 v[116:119], v[172:175], v[188:191], v[116:119]
	v_mfma_f32_16x16x32_bf16 v[88:91], v[152:155], v[210:213], v[88:91]
	v_mfma_f32_16x16x32_bf16 v[84:87], v[172:175], v[210:213], v[84:87]
	v_mfma_f32_16x16x32_bf16 v[72:75], v[152:155], v[218:221], v[72:75]
	v_mfma_f32_16x16x32_bf16 v[68:71], v[172:175], v[218:221], v[68:71]
	s_barrier
	s_add_i32 s14, s69, s24
	v_lshl_add_u64 v[236:237], s[18:19], 0, v[160:161]
	s_mov_b32 m0, s14
	ds_read_b128 v[176:179], v208 offset:16384
	ds_read_b128 v[180:183], v208 offset:17408
	ds_read_b128 v[184:187], v208 offset:18432
	ds_read_b128 v[188:191], v208 offset:19456
	ds_read_b128 v[192:195], v208 offset:20480
	ds_read_b128 v[210:213], v208 offset:21504
	ds_read_b128 v[214:217], v208 offset:22528
	ds_read_b128 v[218:221], v208 offset:23552
	global_load_lds_dwordx4 v[236:237], off
	s_add_i32 m0, s14, 0x2000
	s_add_u32 s14, s18, 0xb0000
	v_lshl_add_u64 v[238:239], s[18:19], 0, v[156:157]
	s_addc_u32 s15, s19, 0
	s_add_i32 s69, s70, s24
	global_load_lds_dwordx4 v[238:239], off
	v_lshl_add_u64 v[240:241], s[14:15], 0, v[160:161]
	s_mov_b32 m0, s69
	v_lshl_add_u64 v[242:243], s[20:21], 0, v[158:159]
	global_load_lds_dwordx4 v[240:241], off
	v_lshl_add_u64 v[240:241], s[14:15], 0, v[156:157]
	s_add_i32 m0, s69, 0x2000
	s_nop 0
	global_load_lds_dwordx4 v[240:241], off
	v_lshl_add_u64 v[240:241], s[20:21], 0, v[162:163]
	s_mov_b32 m0, s25
	s_nop 0
	global_load_lds_dwordx4 v[240:241], off
	s_mov_b32 m0, s26
	s_nop 0
	global_load_lds_dwordx4 v[242:243], off
	s_waitcnt vmcnt(8)
	s_waitcnt lgkmcnt(0)
	s_barrier
	s_waitcnt lgkmcnt(0)
	v_mfma_f32_16x16x32_bf16 v[64:67], v[108:111], v[176:179], v[64:67]
	v_mfma_f32_16x16x32_bf16 v[60:63], v[132:135], v[176:179], v[60:63]
	v_mfma_f32_16x16x32_bf16 v[48:51], v[108:111], v[184:187], v[48:51]
	v_mfma_f32_16x16x32_bf16 v[44:47], v[132:135], v[184:187], v[44:47]
	v_mfma_f32_16x16x32_bf16 v[32:35], v[108:111], v[192:195], v[32:35]
	v_mfma_f32_16x16x32_bf16 v[28:31], v[132:135], v[192:195], v[28:31]
	v_mfma_f32_16x16x32_bf16 v[16:19], v[108:111], v[214:217], v[16:19]
	v_mfma_f32_16x16x32_bf16 v[12:15], v[132:135], v[214:217], v[12:15]
	v_mfma_f32_16x16x32_bf16 v[64:67], v[112:115], v[180:183], v[64:67]
	v_mfma_f32_16x16x32_bf16 v[60:63], v[136:139], v[180:183], v[60:63]
	v_mfma_f32_16x16x32_bf16 v[48:51], v[112:115], v[188:191], v[48:51]
	v_mfma_f32_16x16x32_bf16 v[44:47], v[136:139], v[188:191], v[44:47]
	v_mfma_f32_16x16x32_bf16 v[32:35], v[112:115], v[210:213], v[32:35]
	v_mfma_f32_16x16x32_bf16 v[28:31], v[136:139], v[210:213], v[28:31]
	v_mfma_f32_16x16x32_bf16 v[16:19], v[112:115], v[218:221], v[16:19]
	v_mfma_f32_16x16x32_bf16 v[12:15], v[136:139], v[218:221], v[12:15]
	v_mfma_f32_16x16x32_bf16 v[56:59], v[148:151], v[176:179], v[56:59]
	v_mfma_f32_16x16x32_bf16 v[52:55], v[168:171], v[176:179], v[52:55]
	v_mfma_f32_16x16x32_bf16 v[40:43], v[148:151], v[184:187], v[40:43]
	v_mfma_f32_16x16x32_bf16 v[36:39], v[168:171], v[184:187], v[36:39]
	v_mfma_f32_16x16x32_bf16 v[24:27], v[148:151], v[192:195], v[24:27]
	v_mfma_f32_16x16x32_bf16 v[20:23], v[168:171], v[192:195], v[20:23]
	v_mfma_f32_16x16x32_bf16 v[8:11], v[148:151], v[214:217], v[8:11]
	v_mfma_f32_16x16x32_bf16 v[4:7], v[168:171], v[214:217], v[4:7]
	v_mfma_f32_16x16x32_bf16 v[56:59], v[152:155], v[180:183], v[56:59]
	v_mfma_f32_16x16x32_bf16 v[52:55], v[172:175], v[180:183], v[52:55]
	v_mfma_f32_16x16x32_bf16 v[40:43], v[152:155], v[188:191], v[40:43]
	v_mfma_f32_16x16x32_bf16 v[36:39], v[172:175], v[188:191], v[36:39]
	v_mfma_f32_16x16x32_bf16 v[24:27], v[152:155], v[210:213], v[24:27]
	v_mfma_f32_16x16x32_bf16 v[20:23], v[172:175], v[210:213], v[20:23]
	v_mfma_f32_16x16x32_bf16 v[8:11], v[152:155], v[218:221], v[8:11]
	v_mfma_f32_16x16x32_bf16 v[4:7], v[172:175], v[218:221], v[4:7]
	s_barrier
	s_add_i32 s69, 0, 0x18000
	v_add_u32_e32 v2, s69, v207
	s_add_i32 s70, 0, 0x1c000
	ds_read_b128 v[108:111], v2
	ds_read_b128 v[112:115], v2 offset:1024
	ds_read_b128 v[132:135], v2 offset:2048
	ds_read_b128 v[136:139], v2 offset:3072
	v_add_u32_e32 v2, s70, v207
	ds_read_b128 v[148:151], v2
	ds_read_b128 v[152:155], v2 offset:1024
	ds_read_b128 v[168:171], v2 offset:2048
	ds_read_b128 v[172:175], v2 offset:3072
	s_add_u32 s14, s20, 0xb0000
	s_addc_u32 s15, s21, 0
	s_mov_b32 m0, s27
	v_lshl_add_u64 v[244:245], s[14:15], 0, v[162:163]
	ds_read_b128 v[176:179], v208 offset:32768
	ds_read_b128 v[180:183], v208 offset:33792
	ds_read_b128 v[184:187], v208 offset:34816
	ds_read_b128 v[188:191], v208 offset:35840
	ds_read_b128 v[192:195], v208 offset:36864
	ds_read_b128 v[210:213], v208 offset:37888
	ds_read_b128 v[214:217], v208 offset:38912
	ds_read_b128 v[218:221], v208 offset:39936
	global_load_lds_dwordx4 v[244:245], off
	v_lshl_add_u64 v[244:245], s[14:15], 0, v[158:159]
	s_mov_b32 m0, s28
	s_nop 0
	global_load_lds_dwordx4 v[244:245], off
	s_waitcnt vmcnt(8)
	s_waitcnt lgkmcnt(0)
	s_barrier
	s_waitcnt lgkmcnt(0)
	v_mfma_f32_16x16x32_bf16 v[144:147], v[108:111], v[176:179], v[144:147]
	v_mfma_f32_16x16x32_bf16 v[140:143], v[132:135], v[176:179], v[140:143]
	v_mfma_f32_16x16x32_bf16 v[128:131], v[108:111], v[184:187], v[128:131]
	v_mfma_f32_16x16x32_bf16 v[124:127], v[132:135], v[184:187], v[124:127]
	v_mfma_f32_16x16x32_bf16 v[96:99], v[108:111], v[192:195], v[96:99]
	v_mfma_f32_16x16x32_bf16 v[92:95], v[132:135], v[192:195], v[92:95]
	v_mfma_f32_16x16x32_bf16 v[80:83], v[108:111], v[214:217], v[80:83]
	v_mfma_f32_16x16x32_bf16 v[76:79], v[132:135], v[214:217], v[76:79]
	v_mfma_f32_16x16x32_bf16 v[144:147], v[112:115], v[180:183], v[144:147]
	v_mfma_f32_16x16x32_bf16 v[140:143], v[136:139], v[180:183], v[140:143]
	v_mfma_f32_16x16x32_bf16 v[128:131], v[112:115], v[188:191], v[128:131]
	v_mfma_f32_16x16x32_bf16 v[124:127], v[136:139], v[188:191], v[124:127]
	v_mfma_f32_16x16x32_bf16 v[96:99], v[112:115], v[210:213], v[96:99]
	v_mfma_f32_16x16x32_bf16 v[92:95], v[136:139], v[210:213], v[92:95]
	v_mfma_f32_16x16x32_bf16 v[80:83], v[112:115], v[218:221], v[80:83]
	v_mfma_f32_16x16x32_bf16 v[76:79], v[136:139], v[218:221], v[76:79]
	v_mfma_f32_16x16x32_bf16 v[104:107], v[148:151], v[176:179], v[104:107]
	v_mfma_f32_16x16x32_bf16 v[100:103], v[168:171], v[176:179], v[100:103]
	v_mfma_f32_16x16x32_bf16 v[120:123], v[148:151], v[184:187], v[120:123]
	v_mfma_f32_16x16x32_bf16 v[116:119], v[168:171], v[184:187], v[116:119]
	v_mfma_f32_16x16x32_bf16 v[88:91], v[148:151], v[192:195], v[88:91]
	v_mfma_f32_16x16x32_bf16 v[84:87], v[168:171], v[192:195], v[84:87]
	v_mfma_f32_16x16x32_bf16 v[72:75], v[148:151], v[214:217], v[72:75]
	v_mfma_f32_16x16x32_bf16 v[68:71], v[168:171], v[214:217], v[68:71]
	v_mfma_f32_16x16x32_bf16 v[104:107], v[152:155], v[180:183], v[104:107]
	v_mfma_f32_16x16x32_bf16 v[100:103], v[172:175], v[180:183], v[100:103]
	v_mfma_f32_16x16x32_bf16 v[120:123], v[152:155], v[188:191], v[120:123]
	v_mfma_f32_16x16x32_bf16 v[116:119], v[172:175], v[188:191], v[116:119]
	v_mfma_f32_16x16x32_bf16 v[88:91], v[152:155], v[210:213], v[88:91]
	v_mfma_f32_16x16x32_bf16 v[84:87], v[172:175], v[210:213], v[84:87]
	v_mfma_f32_16x16x32_bf16 v[72:75], v[152:155], v[218:221], v[72:75]
	v_mfma_f32_16x16x32_bf16 v[68:71], v[172:175], v[218:221], v[68:71]
	s_barrier
	s_add_i32 s14, s69, s24
	v_lshl_add_u64 v[236:237], v[236:237], 0, s[96:97]
	s_mov_b32 m0, s14
	ds_read_b128 v[176:179], v208 offset:49152
	ds_read_b128 v[180:183], v208 offset:50176
	ds_read_b128 v[184:187], v208 offset:51200
	ds_read_b128 v[188:191], v208 offset:52224
	ds_read_b128 v[192:195], v208 offset:53248
	ds_read_b128 v[210:213], v208 offset:54272
	ds_read_b128 v[214:217], v208 offset:55296
	ds_read_b128 v[218:221], v208 offset:56320
	global_load_lds_dwordx4 v[236:237], off
	s_add_i32 m0, s14, 0x2000
	s_add_u32 s14, s18, 0xb0080
	v_lshl_add_u64 v[236:237], v[238:239], 0, s[96:97]
	s_addc_u32 s15, s19, 0
	s_add_i32 s18, s70, s24
	global_load_lds_dwordx4 v[236:237], off
	v_lshl_add_u64 v[236:237], s[14:15], 0, v[160:161]
	s_mov_b32 m0, s18
	s_nop 0
	global_load_lds_dwordx4 v[236:237], off
	v_lshl_add_u64 v[236:237], s[14:15], 0, v[156:157]
	s_add_i32 m0, s18, 0x2000
	s_nop 0
	global_load_lds_dwordx4 v[236:237], off
	v_lshl_add_u64 v[236:237], v[240:241], 0, s[96:97]
	s_mov_b32 m0, s31
	s_nop 0
	global_load_lds_dwordx4 v[236:237], off
	v_lshl_add_u64 v[236:237], v[242:243], 0, s[96:97]
	s_mov_b32 m0, s34
	s_nop 0
	global_load_lds_dwordx4 v[236:237], off
	s_waitcnt vmcnt(8)
	s_waitcnt lgkmcnt(0)
	s_barrier
	s_waitcnt lgkmcnt(0)
	v_mfma_f32_16x16x32_bf16 v[64:67], v[108:111], v[176:179], v[64:67]
	v_mfma_f32_16x16x32_bf16 v[60:63], v[132:135], v[176:179], v[60:63]
	v_mfma_f32_16x16x32_bf16 v[48:51], v[108:111], v[184:187], v[48:51]
	v_mfma_f32_16x16x32_bf16 v[44:47], v[132:135], v[184:187], v[44:47]
	v_mfma_f32_16x16x32_bf16 v[32:35], v[108:111], v[192:195], v[32:35]
	v_mfma_f32_16x16x32_bf16 v[28:31], v[132:135], v[192:195], v[28:31]
	v_mfma_f32_16x16x32_bf16 v[16:19], v[108:111], v[214:217], v[16:19]
	v_mfma_f32_16x16x32_bf16 v[12:15], v[132:135], v[214:217], v[12:15]
	v_mfma_f32_16x16x32_bf16 v[64:67], v[112:115], v[180:183], v[64:67]
	v_mfma_f32_16x16x32_bf16 v[60:63], v[136:139], v[180:183], v[60:63]
	v_mfma_f32_16x16x32_bf16 v[48:51], v[112:115], v[188:191], v[48:51]
	v_mfma_f32_16x16x32_bf16 v[44:47], v[136:139], v[188:191], v[44:47]
	v_mfma_f32_16x16x32_bf16 v[32:35], v[112:115], v[210:213], v[32:35]
	v_mfma_f32_16x16x32_bf16 v[28:31], v[136:139], v[210:213], v[28:31]
	v_mfma_f32_16x16x32_bf16 v[16:19], v[112:115], v[218:221], v[16:19]
	v_mfma_f32_16x16x32_bf16 v[12:15], v[136:139], v[218:221], v[12:15]
	v_mfma_f32_16x16x32_bf16 v[56:59], v[148:151], v[176:179], v[56:59]
	v_mfma_f32_16x16x32_bf16 v[52:55], v[168:171], v[176:179], v[52:55]
	v_mfma_f32_16x16x32_bf16 v[40:43], v[148:151], v[184:187], v[40:43]
	v_mfma_f32_16x16x32_bf16 v[36:39], v[168:171], v[184:187], v[36:39]
	v_mfma_f32_16x16x32_bf16 v[24:27], v[148:151], v[192:195], v[24:27]
	v_mfma_f32_16x16x32_bf16 v[20:23], v[168:171], v[192:195], v[20:23]
	v_mfma_f32_16x16x32_bf16 v[8:11], v[148:151], v[214:217], v[8:11]
	v_mfma_f32_16x16x32_bf16 v[4:7], v[168:171], v[214:217], v[4:7]
	v_mfma_f32_16x16x32_bf16 v[56:59], v[152:155], v[180:183], v[56:59]
	v_mfma_f32_16x16x32_bf16 v[52:55], v[172:175], v[180:183], v[52:55]
	v_mfma_f32_16x16x32_bf16 v[40:43], v[152:155], v[188:191], v[40:43]
	v_mfma_f32_16x16x32_bf16 v[36:39], v[172:175], v[188:191], v[36:39]
	v_mfma_f32_16x16x32_bf16 v[24:27], v[152:155], v[210:213], v[24:27]
	v_mfma_f32_16x16x32_bf16 v[20:23], v[172:175], v[210:213], v[20:23]
	v_mfma_f32_16x16x32_bf16 v[8:11], v[152:155], v[218:221], v[8:11]
	v_mfma_f32_16x16x32_bf16 v[4:7], v[172:175], v[218:221], v[4:7]
	s_barrier
	s_add_i32 s68, s68, 2
	s_add_u32 s66, s66, 0x100
	s_addc_u32 s67, s67, 0
	s_cmp_gt_u32 s68, 41
	s_mov_b64 s[14:15], s[16:17]
	s_cbranch_scc0 .LBB0_156
	s_and_b64 vcc, exec, s[50:51]
	s_cbranch_vccz .LBB0_159
	s_barrier

.LBB0_316:
	s_add_u32 s30, s28, 0xfffc0080
	s_addc_u32 s31, s29, -1
	s_add_i32 s63, 0, 0x10000
	s_cmp_eq_u32 s62, 12
	s_cselect_b32 s35, s25, s31
	s_cselect_b32 s34, s58, s30
	v_add_u32_e32 v142, s63, v145
	s_cselect_b32 s31, s23, s61
	s_cselect_b32 s30, s59, s60
	s_add_i32 s66, 0, 0x14000
	ds_read_b128 v[148:151], v142
	ds_read_b128 v[152:155], v142 offset:1024
	ds_read_b128 v[156:159], v142 offset:2048
	ds_read_b128 v[160:163], v142 offset:3072
	v_add_u32_e32 v142, s66, v145
	ds_read_b128 v[164:167], v142
	ds_read_b128 v[168:171], v142 offset:1024
	ds_read_b128 v[172:175], v142 offset:2048
	ds_read_b128 v[176:179], v142 offset:3072
	v_lshl_add_u64 v[142:143], s[28:29], 0, v[138:139]
	s_add_i32 m0, s45, 0xc000
	ds_read_b128 v[180:183], v146
	ds_read_b128 v[184:187], v146 offset:1024
	ds_read_b128 v[188:191], v146 offset:2048
	ds_read_b128 v[192:195], v146 offset:3072
	ds_read_b128 v[206:209], v146 offset:4096
	ds_read_b128 v[210:213], v146 offset:5120
	ds_read_b128 v[214:217], v146 offset:6144
	ds_read_b128 v[218:221], v146 offset:7168
	global_load_lds_dwordx4 v[142:143], off
	v_lshl_add_u64 v[142:143], s[28:29], 0, v[140:141]
	s_add_i32 m0, s45, 0xe000
	s_nop 0
	global_load_lds_dwordx4 v[142:143], off
	s_waitcnt vmcnt(8)
	s_waitcnt lgkmcnt(0)
	s_barrier
	s_waitcnt lgkmcnt(0)
	v_mfma_f32_16x16x32_bf16 v[128:131], v[148:151], v[180:183], v[128:131]
	v_mfma_f32_16x16x32_bf16 v[120:123], v[156:159], v[180:183], v[120:123]
	v_mfma_f32_16x16x32_bf16 v[112:115], v[148:151], v[188:191], v[112:115]
	v_mfma_f32_16x16x32_bf16 v[104:107], v[156:159], v[188:191], v[104:107]
	v_mfma_f32_16x16x32_bf16 v[96:99], v[148:151], v[206:209], v[96:99]
	v_mfma_f32_16x16x32_bf16 v[88:91], v[156:159], v[206:209], v[88:91]
	v_mfma_f32_16x16x32_bf16 v[80:83], v[148:151], v[214:217], v[80:83]
	v_mfma_f32_16x16x32_bf16 v[72:75], v[156:159], v[214:217], v[72:75]
	v_mfma_f32_16x16x32_bf16 v[128:131], v[152:155], v[184:187], v[128:131]
	v_mfma_f32_16x16x32_bf16 v[120:123], v[160:163], v[184:187], v[120:123]
	v_mfma_f32_16x16x32_bf16 v[112:115], v[152:155], v[192:195], v[112:115]
	v_mfma_f32_16x16x32_bf16 v[104:107], v[160:163], v[192:195], v[104:107]
	v_mfma_f32_16x16x32_bf16 v[96:99], v[152:155], v[210:213], v[96:99]
	v_mfma_f32_16x16x32_bf16 v[88:91], v[160:163], v[210:213], v[88:91]
	v_mfma_f32_16x16x32_bf16 v[80:83], v[152:155], v[218:221], v[80:83]
	v_mfma_f32_16x16x32_bf16 v[72:75], v[160:163], v[218:221], v[72:75]
	v_mfma_f32_16x16x32_bf16 v[124:127], v[164:167], v[180:183], v[124:127]
	v_mfma_f32_16x16x32_bf16 v[116:119], v[172:175], v[180:183], v[116:119]
	v_mfma_f32_16x16x32_bf16 v[108:111], v[164:167], v[188:191], v[108:111]
	v_mfma_f32_16x16x32_bf16 v[100:103], v[172:175], v[188:191], v[100:103]
	v_mfma_f32_16x16x32_bf16 v[92:95], v[164:167], v[206:209], v[92:95]
	v_mfma_f32_16x16x32_bf16 v[84:87], v[172:175], v[206:209], v[84:87]
	v_mfma_f32_16x16x32_bf16 v[76:79], v[164:167], v[214:217], v[76:79]
	v_mfma_f32_16x16x32_bf16 v[68:71], v[172:175], v[214:217], v[68:71]
	v_mfma_f32_16x16x32_bf16 v[124:127], v[168:171], v[184:187], v[124:127]
	v_mfma_f32_16x16x32_bf16 v[116:119], v[176:179], v[184:187], v[116:119]
	v_mfma_f32_16x16x32_bf16 v[108:111], v[168:171], v[192:195], v[108:111]
	v_mfma_f32_16x16x32_bf16 v[100:103], v[176:179], v[192:195], v[100:103]
	v_mfma_f32_16x16x32_bf16 v[92:95], v[168:171], v[210:213], v[92:95]
	v_mfma_f32_16x16x32_bf16 v[84:87], v[176:179], v[210:213], v[84:87]
	v_mfma_f32_16x16x32_bf16 v[76:79], v[168:171], v[218:221], v[76:79]
	v_mfma_f32_16x16x32_bf16 v[68:71], v[176:179], v[218:221], v[68:71]
	s_barrier
	s_add_i32 s63, s63, s36
	v_lshl_add_u64 v[142:143], s[30:31], 0, v[2:3]
	s_mov_b32 m0, s63
	ds_read_b128 v[180:183], v146 offset:16384
	ds_read_b128 v[184:187], v146 offset:17408
	ds_read_b128 v[188:191], v146 offset:18432
	ds_read_b128 v[192:195], v146 offset:19456
	ds_read_b128 v[206:209], v146 offset:20480
	ds_read_b128 v[210:213], v146 offset:21504
	ds_read_b128 v[214:217], v146 offset:22528
	ds_read_b128 v[218:221], v146 offset:23552
	global_load_lds_dwordx4 v[142:143], off
	s_add_i32 m0, s63, 0x2000
	s_add_u32 s64, s30, 0x40000
	v_lshl_add_u64 v[236:237], s[30:31], 0, v[132:133]
	s_addc_u32 s65, s31, 0
	s_add_i32 s63, s66, s36
	global_load_lds_dwordx4 v[236:237], off
	v_lshl_add_u64 v[238:239], s[64:65], 0, v[2:3]
	s_mov_b32 m0, s63
	v_lshl_add_u64 v[240:241], s[34:35], 0, v[134:135]
	global_load_lds_dwordx4 v[238:239], off
	v_lshl_add_u64 v[238:239], s[64:65], 0, v[132:133]
	s_add_i32 m0, s63, 0x2000
	s_nop 0
	global_load_lds_dwordx4 v[238:239], off
	v_lshl_add_u64 v[238:239], s[34:35], 0, v[136:137]
	s_mov_b32 m0, s45
	s_nop 0
	global_load_lds_dwordx4 v[238:239], off
	s_mov_b32 m0, s46
	s_nop 0
	global_load_lds_dwordx4 v[240:241], off
	s_waitcnt vmcnt(8)
	s_waitcnt lgkmcnt(0)
	s_barrier
	s_waitcnt lgkmcnt(0)
	v_mfma_f32_16x16x32_bf16 v[64:67], v[148:151], v[180:183], v[64:67]
	v_mfma_f32_16x16x32_bf16 v[56:59], v[156:159], v[180:183], v[56:59]
	v_mfma_f32_16x16x32_bf16 v[48:51], v[148:151], v[188:191], v[48:51]
	v_mfma_f32_16x16x32_bf16 v[40:43], v[156:159], v[188:191], v[40:43]
	v_mfma_f32_16x16x32_bf16 v[32:35], v[148:151], v[206:209], v[32:35]
	v_mfma_f32_16x16x32_bf16 v[24:27], v[156:159], v[206:209], v[24:27]
	v_mfma_f32_16x16x32_bf16 v[16:19], v[148:151], v[214:217], v[16:19]
	v_mfma_f32_16x16x32_bf16 v[8:11], v[156:159], v[214:217], v[8:11]
	v_mfma_f32_16x16x32_bf16 v[64:67], v[152:155], v[184:187], v[64:67]
	v_mfma_f32_16x16x32_bf16 v[56:59], v[160:163], v[184:187], v[56:59]
	v_mfma_f32_16x16x32_bf16 v[48:51], v[152:155], v[192:195], v[48:51]
	v_mfma_f32_16x16x32_bf16 v[40:43], v[160:163], v[192:195], v[40:43]
	v_mfma_f32_16x16x32_bf16 v[32:35], v[152:155], v[210:213], v[32:35]
	v_mfma_f32_16x16x32_bf16 v[24:27], v[160:163], v[210:213], v[24:27]
	v_mfma_f32_16x16x32_bf16 v[16:19], v[152:155], v[218:221], v[16:19]
	v_mfma_f32_16x16x32_bf16 v[8:11], v[160:163], v[218:221], v[8:11]
	v_mfma_f32_16x16x32_bf16 v[60:63], v[164:167], v[180:183], v[60:63]
	v_mfma_f32_16x16x32_bf16 v[52:55], v[172:175], v[180:183], v[52:55]
	v_mfma_f32_16x16x32_bf16 v[44:47], v[164:167], v[188:191], v[44:47]
	v_mfma_f32_16x16x32_bf16 v[36:39], v[172:175], v[188:191], v[36:39]
	v_mfma_f32_16x16x32_bf16 v[28:31], v[164:167], v[206:209], v[28:31]
	v_mfma_f32_16x16x32_bf16 v[20:23], v[172:175], v[206:209], v[20:23]
	v_mfma_f32_16x16x32_bf16 v[12:15], v[164:167], v[214:217], v[12:15]
	v_mfma_f32_16x16x32_bf16 v[4:7], v[172:175], v[214:217], v[4:7]
	v_mfma_f32_16x16x32_bf16 v[60:63], v[168:171], v[184:187], v[60:63]
	v_mfma_f32_16x16x32_bf16 v[52:55], v[176:179], v[184:187], v[52:55]
	v_mfma_f32_16x16x32_bf16 v[44:47], v[168:171], v[192:195], v[44:47]
	v_mfma_f32_16x16x32_bf16 v[36:39], v[176:179], v[192:195], v[36:39]
	v_mfma_f32_16x16x32_bf16 v[28:31], v[168:171], v[210:213], v[28:31]
	v_mfma_f32_16x16x32_bf16 v[20:23], v[176:179], v[210:213], v[20:23]
	v_mfma_f32_16x16x32_bf16 v[12:15], v[168:171], v[218:221], v[12:15]
	v_mfma_f32_16x16x32_bf16 v[4:7], v[176:179], v[218:221], v[4:7]
	s_barrier
	s_add_i32 s63, 0, 0x18000
	v_add_u32_e32 v147, s63, v145
	s_add_i32 s64, 0, 0x1c000
	ds_read_b128 v[148:151], v147
	ds_read_b128 v[152:155], v147 offset:1024
	ds_read_b128 v[156:159], v147 offset:2048
	ds_read_b128 v[160:163], v147 offset:3072
	v_add_u32_e32 v147, s64, v145
	ds_read_b128 v[164:167], v147
	ds_read_b128 v[168:171], v147 offset:1024
	ds_read_b128 v[172:175], v147 offset:2048
	ds_read_b128 v[176:179], v147 offset:3072
	s_add_u32 s34, s34, 0x40000
	s_addc_u32 s35, s35, 0
	s_mov_b32 m0, s47
	v_lshl_add_u64 v[242:243], s[34:35], 0, v[136:137]
	ds_read_b128 v[180:183], v146 offset:32768
	ds_read_b128 v[184:187], v146 offset:33792
	ds_read_b128 v[188:191], v146 offset:34816
	ds_read_b128 v[192:195], v146 offset:35840
	ds_read_b128 v[206:209], v146 offset:36864
	ds_read_b128 v[210:213], v146 offset:37888
	ds_read_b128 v[214:217], v146 offset:38912
	ds_read_b128 v[218:221], v146 offset:39936
	global_load_lds_dwordx4 v[242:243], off
	v_lshl_add_u64 v[242:243], s[34:35], 0, v[134:135]
	s_mov_b32 m0, s48
	s_nop 0
	global_load_lds_dwordx4 v[242:243], off
	s_waitcnt vmcnt(8)
	s_waitcnt lgkmcnt(0)
	s_barrier
	s_waitcnt lgkmcnt(0)
	v_mfma_f32_16x16x32_bf16 v[128:131], v[148:151], v[180:183], v[128:131]
	v_mfma_f32_16x16x32_bf16 v[120:123], v[156:159], v[180:183], v[120:123]
	v_mfma_f32_16x16x32_bf16 v[112:115], v[148:151], v[188:191], v[112:115]
	v_mfma_f32_16x16x32_bf16 v[104:107], v[156:159], v[188:191], v[104:107]
	v_mfma_f32_16x16x32_bf16 v[96:99], v[148:151], v[206:209], v[96:99]
	v_mfma_f32_16x16x32_bf16 v[88:91], v[156:159], v[206:209], v[88:91]
	v_mfma_f32_16x16x32_bf16 v[80:83], v[148:151], v[214:217], v[80:83]
	v_mfma_f32_16x16x32_bf16 v[72:75], v[156:159], v[214:217], v[72:75]
	v_mfma_f32_16x16x32_bf16 v[128:131], v[152:155], v[184:187], v[128:131]
	v_mfma_f32_16x16x32_bf16 v[120:123], v[160:163], v[184:187], v[120:123]
	v_mfma_f32_16x16x32_bf16 v[112:115], v[152:155], v[192:195], v[112:115]
	v_mfma_f32_16x16x32_bf16 v[104:107], v[160:163], v[192:195], v[104:107]
	v_mfma_f32_16x16x32_bf16 v[96:99], v[152:155], v[210:213], v[96:99]
	v_mfma_f32_16x16x32_bf16 v[88:91], v[160:163], v[210:213], v[88:91]
	v_mfma_f32_16x16x32_bf16 v[80:83], v[152:155], v[218:221], v[80:83]
	v_mfma_f32_16x16x32_bf16 v[72:75], v[160:163], v[218:221], v[72:75]
	v_mfma_f32_16x16x32_bf16 v[124:127], v[164:167], v[180:183], v[124:127]
	v_mfma_f32_16x16x32_bf16 v[116:119], v[172:175], v[180:183], v[116:119]
	v_mfma_f32_16x16x32_bf16 v[108:111], v[164:167], v[188:191], v[108:111]
	v_mfma_f32_16x16x32_bf16 v[100:103], v[172:175], v[188:191], v[100:103]
	v_mfma_f32_16x16x32_bf16 v[92:95], v[164:167], v[206:209], v[92:95]
	v_mfma_f32_16x16x32_bf16 v[84:87], v[172:175], v[206:209], v[84:87]
	v_mfma_f32_16x16x32_bf16 v[76:79], v[164:167], v[214:217], v[76:79]
	v_mfma_f32_16x16x32_bf16 v[68:71], v[172:175], v[214:217], v[68:71]
	v_mfma_f32_16x16x32_bf16 v[124:127], v[168:171], v[184:187], v[124:127]
	v_mfma_f32_16x16x32_bf16 v[116:119], v[176:179], v[184:187], v[116:119]
	v_mfma_f32_16x16x32_bf16 v[108:111], v[168:171], v[192:195], v[108:111]
	v_mfma_f32_16x16x32_bf16 v[100:103], v[176:179], v[192:195], v[100:103]
	v_mfma_f32_16x16x32_bf16 v[92:95], v[168:171], v[210:213], v[92:95]
	v_mfma_f32_16x16x32_bf16 v[84:87], v[176:179], v[210:213], v[84:87]
	v_mfma_f32_16x16x32_bf16 v[76:79], v[168:171], v[218:221], v[76:79]
	v_mfma_f32_16x16x32_bf16 v[68:71], v[176:179], v[218:221], v[68:71]
	s_barrier
	s_add_i32 s34, s63, s36
	v_lshl_add_u64 v[142:143], v[142:143], 0, s[96:97]
	s_mov_b32 m0, s34
	ds_read_b128 v[180:183], v146 offset:49152
	ds_read_b128 v[184:187], v146 offset:50176
	ds_read_b128 v[188:191], v146 offset:51200
	ds_read_b128 v[192:195], v146 offset:52224
	ds_read_b128 v[206:209], v146 offset:53248
	ds_read_b128 v[210:213], v146 offset:54272
	ds_read_b128 v[214:217], v146 offset:55296
	ds_read_b128 v[218:221], v146 offset:56320
	global_load_lds_dwordx4 v[142:143], off
	s_add_i32 m0, s34, 0x2000
	s_add_u32 s30, s30, 0x40080
	v_lshl_add_u64 v[142:143], v[236:237], 0, s[96:97]
	s_addc_u32 s31, s31, 0
	s_add_i32 s34, s64, s36
	global_load_lds_dwordx4 v[142:143], off
	v_lshl_add_u64 v[142:143], s[30:31], 0, v[2:3]
	s_mov_b32 m0, s34
	s_nop 0
	global_load_lds_dwordx4 v[142:143], off
	v_lshl_add_u64 v[142:143], s[30:31], 0, v[132:133]
	s_add_i32 m0, s34, 0x2000
	s_nop 0
	global_load_lds_dwordx4 v[142:143], off
	v_lshl_add_u64 v[142:143], v[238:239], 0, s[96:97]
	s_mov_b32 m0, s51
	s_nop 0
	global_load_lds_dwordx4 v[142:143], off
	v_lshl_add_u64 v[142:143], v[240:241], 0, s[96:97]
	s_mov_b32 m0, s52
	s_nop 0
	global_load_lds_dwordx4 v[142:143], off
	s_waitcnt vmcnt(8)
	s_waitcnt lgkmcnt(0)
	s_barrier
	s_waitcnt lgkmcnt(0)
	v_mfma_f32_16x16x32_bf16 v[64:67], v[148:151], v[180:183], v[64:67]
	v_mfma_f32_16x16x32_bf16 v[56:59], v[156:159], v[180:183], v[56:59]
	v_mfma_f32_16x16x32_bf16 v[48:51], v[148:151], v[188:191], v[48:51]
	v_mfma_f32_16x16x32_bf16 v[40:43], v[156:159], v[188:191], v[40:43]
	v_mfma_f32_16x16x32_bf16 v[32:35], v[148:151], v[206:209], v[32:35]
	v_mfma_f32_16x16x32_bf16 v[24:27], v[156:159], v[206:209], v[24:27]
	v_mfma_f32_16x16x32_bf16 v[16:19], v[148:151], v[214:217], v[16:19]
	v_mfma_f32_16x16x32_bf16 v[8:11], v[156:159], v[214:217], v[8:11]
	v_mfma_f32_16x16x32_bf16 v[64:67], v[152:155], v[184:187], v[64:67]
	v_mfma_f32_16x16x32_bf16 v[56:59], v[160:163], v[184:187], v[56:59]
	v_mfma_f32_16x16x32_bf16 v[48:51], v[152:155], v[192:195], v[48:51]
	v_mfma_f32_16x16x32_bf16 v[40:43], v[160:163], v[192:195], v[40:43]
	v_mfma_f32_16x16x32_bf16 v[32:35], v[152:155], v[210:213], v[32:35]
	v_mfma_f32_16x16x32_bf16 v[24:27], v[160:163], v[210:213], v[24:27]
	v_mfma_f32_16x16x32_bf16 v[16:19], v[152:155], v[218:221], v[16:19]
	v_mfma_f32_16x16x32_bf16 v[8:11], v[160:163], v[218:221], v[8:11]
	v_mfma_f32_16x16x32_bf16 v[60:63], v[164:167], v[180:183], v[60:63]
	v_mfma_f32_16x16x32_bf16 v[52:55], v[172:175], v[180:183], v[52:55]
	v_mfma_f32_16x16x32_bf16 v[44:47], v[164:167], v[188:191], v[44:47]
	v_mfma_f32_16x16x32_bf16 v[36:39], v[172:175], v[188:191], v[36:39]
	v_mfma_f32_16x16x32_bf16 v[28:31], v[164:167], v[206:209], v[28:31]
	v_mfma_f32_16x16x32_bf16 v[20:23], v[172:175], v[206:209], v[20:23]
	v_mfma_f32_16x16x32_bf16 v[12:15], v[164:167], v[214:217], v[12:15]
	v_mfma_f32_16x16x32_bf16 v[4:7], v[172:175], v[214:217], v[4:7]
	v_mfma_f32_16x16x32_bf16 v[60:63], v[168:171], v[184:187], v[60:63]
	v_mfma_f32_16x16x32_bf16 v[52:55], v[176:179], v[184:187], v[52:55]
	v_mfma_f32_16x16x32_bf16 v[44:47], v[168:171], v[192:195], v[44:47]
	v_mfma_f32_16x16x32_bf16 v[36:39], v[176:179], v[192:195], v[36:39]
	v_mfma_f32_16x16x32_bf16 v[28:31], v[168:171], v[210:213], v[28:31]
	v_mfma_f32_16x16x32_bf16 v[20:23], v[176:179], v[210:213], v[20:23]
	v_mfma_f32_16x16x32_bf16 v[12:15], v[168:171], v[218:221], v[12:15]
	v_mfma_f32_16x16x32_bf16 v[4:7], v[176:179], v[218:221], v[4:7]
	s_barrier
	s_add_i32 s62, s62, 2
	s_add_u32 s28, s28, 0x100
	s_addc_u32 s29, s29, 0
	s_add_u32 s60, s60, 0x100
	s_addc_u32 s61, s61, 0
	s_cmp_gt_u32 s62, 13
	s_cbranch_scc0 .LBB0_316
	s_and_b64 vcc, exec, s[16:17]
	s_cbranch_vccz .LBB0_319
	s_barrier

.LBB0_340:
	s_add_u32 s20, s18, 0xfffc0080
	s_addc_u32 s21, s19, -1
	s_add_i32 s60, 0, 0x10000
	s_cmp_eq_u32 s59, 12
	s_cselect_b32 s23, s43, s21
	s_cselect_b32 s22, s53, s20
	s_cselect_b32 s21, s51, s58
	s_cselect_b32 s20, s56, s57
	s_add_i32 s62, 0, 0x14000
	v_add_u32_e32 v136, s60, v183
	v_add_u32_e32 v170, s62, v183
	ds_read_b128 v[108:111], v136
	ds_read_b128 v[112:115], v136 offset:1024
	ds_read_b128 v[132:135], v136 offset:2048
	ds_read_b128 v[136:139], v136 offset:3072
	ds_read_b128 v[140:143], v170
	ds_read_b128 v[144:147], v170 offset:1024
	ds_read_b128 v[166:169], v170 offset:2048
	ds_read_b128 v[170:173], v170 offset:3072
	v_lshl_add_u64 v[194:195], s[18:19], 0, v[162:163]
	s_add_i32 m0, s26, 0xc000
	ds_read_b128 v[174:177], v184
	ds_read_b128 v[178:181], v184 offset:1024
	ds_read_b128 v[186:189], v184 offset:2048
	ds_read_b128 v[190:193], v184 offset:3072
	ds_read_b128 v[206:209], v184 offset:4096
	ds_read_b128 v[210:213], v184 offset:5120
	ds_read_b128 v[214:217], v184 offset:6144
	ds_read_b128 v[218:221], v184 offset:7168
	global_load_lds_dwordx4 v[194:195], off
	v_lshl_add_u64 v[194:195], s[18:19], 0, v[164:165]
	s_add_i32 m0, s26, 0xe000
	s_nop 0
	global_load_lds_dwordx4 v[194:195], off
	s_waitcnt vmcnt(8)
	s_waitcnt lgkmcnt(0)
	s_barrier
	s_waitcnt lgkmcnt(0)
	v_mfma_f32_16x16x32_bf16 v[152:155], v[108:111], v[174:177], v[152:155]
	v_mfma_f32_16x16x32_bf16 v[148:151], v[132:135], v[174:177], v[148:151]
	v_mfma_f32_16x16x32_bf16 v[128:131], v[108:111], v[186:189], v[128:131]
	v_mfma_f32_16x16x32_bf16 v[124:127], v[132:135], v[186:189], v[124:127]
	v_mfma_f32_16x16x32_bf16 v[96:99], v[108:111], v[206:209], v[96:99]
	v_mfma_f32_16x16x32_bf16 v[92:95], v[132:135], v[206:209], v[92:95]
	v_mfma_f32_16x16x32_bf16 v[80:83], v[108:111], v[214:217], v[80:83]
	v_mfma_f32_16x16x32_bf16 v[76:79], v[132:135], v[214:217], v[76:79]
	v_mfma_f32_16x16x32_bf16 v[152:155], v[112:115], v[178:181], v[152:155]
	v_mfma_f32_16x16x32_bf16 v[148:151], v[136:139], v[178:181], v[148:151]
	v_mfma_f32_16x16x32_bf16 v[128:131], v[112:115], v[190:193], v[128:131]
	v_mfma_f32_16x16x32_bf16 v[124:127], v[136:139], v[190:193], v[124:127]
	v_mfma_f32_16x16x32_bf16 v[96:99], v[112:115], v[210:213], v[96:99]
	v_mfma_f32_16x16x32_bf16 v[92:95], v[136:139], v[210:213], v[92:95]
	v_mfma_f32_16x16x32_bf16 v[80:83], v[112:115], v[218:221], v[80:83]
	v_mfma_f32_16x16x32_bf16 v[76:79], v[136:139], v[218:221], v[76:79]
	v_mfma_f32_16x16x32_bf16 v[104:107], v[140:143], v[174:177], v[104:107]
	v_mfma_f32_16x16x32_bf16 v[100:103], v[166:169], v[174:177], v[100:103]
	v_mfma_f32_16x16x32_bf16 v[120:123], v[140:143], v[186:189], v[120:123]
	v_mfma_f32_16x16x32_bf16 v[116:119], v[166:169], v[186:189], v[116:119]
	v_mfma_f32_16x16x32_bf16 v[88:91], v[140:143], v[206:209], v[88:91]
	v_mfma_f32_16x16x32_bf16 v[84:87], v[166:169], v[206:209], v[84:87]
	v_mfma_f32_16x16x32_bf16 v[72:75], v[140:143], v[214:217], v[72:75]
	v_mfma_f32_16x16x32_bf16 v[68:71], v[166:169], v[214:217], v[68:71]
	v_mfma_f32_16x16x32_bf16 v[104:107], v[144:147], v[178:181], v[104:107]
	v_mfma_f32_16x16x32_bf16 v[100:103], v[170:173], v[178:181], v[100:103]
	v_mfma_f32_16x16x32_bf16 v[120:123], v[144:147], v[190:193], v[120:123]
	v_mfma_f32_16x16x32_bf16 v[116:119], v[170:173], v[190:193], v[116:119]
	v_mfma_f32_16x16x32_bf16 v[88:91], v[144:147], v[210:213], v[88:91]
	v_mfma_f32_16x16x32_bf16 v[84:87], v[170:173], v[210:213], v[84:87]
	v_mfma_f32_16x16x32_bf16 v[72:75], v[144:147], v[218:221], v[72:75]
	v_mfma_f32_16x16x32_bf16 v[68:71], v[170:173], v[218:221], v[68:71]
	s_barrier
	s_add_i32 s60, s60, s25
	v_lshl_add_u64 v[194:195], s[20:21], 0, v[2:3]
	s_mov_b32 m0, s60
	ds_read_b128 v[174:177], v184 offset:16384
	ds_read_b128 v[178:181], v184 offset:17408
	ds_read_b128 v[186:189], v184 offset:18432
	ds_read_b128 v[190:193], v184 offset:19456
	ds_read_b128 v[206:209], v184 offset:20480
	ds_read_b128 v[210:213], v184 offset:21504
	ds_read_b128 v[214:217], v184 offset:22528
	ds_read_b128 v[218:221], v184 offset:23552
	global_load_lds_dwordx4 v[194:195], off
	s_add_i32 m0, s60, 0x2000
	s_add_u32 s60, s20, 0x40000
	v_lshl_add_u64 v[236:237], s[20:21], 0, v[156:157]
	s_addc_u32 s61, s21, 0
	s_add_i32 s62, s62, s25
	global_load_lds_dwordx4 v[236:237], off
	v_lshl_add_u64 v[238:239], s[60:61], 0, v[2:3]
	s_mov_b32 m0, s62
	v_lshl_add_u64 v[240:241], s[22:23], 0, v[158:159]
	global_load_lds_dwordx4 v[238:239], off
	v_lshl_add_u64 v[238:239], s[60:61], 0, v[156:157]
	s_add_i32 m0, s62, 0x2000
	s_nop 0
	global_load_lds_dwordx4 v[238:239], off
	v_lshl_add_u64 v[238:239], s[22:23], 0, v[160:161]
	s_mov_b32 m0, s26
	s_nop 0
	global_load_lds_dwordx4 v[238:239], off
	s_mov_b32 m0, s27
	s_nop 0
	global_load_lds_dwordx4 v[240:241], off
	s_waitcnt vmcnt(8)
	s_waitcnt lgkmcnt(0)
	s_barrier
	s_waitcnt lgkmcnt(0)
	v_mfma_f32_16x16x32_bf16 v[64:67], v[108:111], v[174:177], v[64:67]
	v_mfma_f32_16x16x32_bf16 v[60:63], v[132:135], v[174:177], v[60:63]
	v_mfma_f32_16x16x32_bf16 v[48:51], v[108:111], v[186:189], v[48:51]
	v_mfma_f32_16x16x32_bf16 v[44:47], v[132:135], v[186:189], v[44:47]
	v_mfma_f32_16x16x32_bf16 v[32:35], v[108:111], v[206:209], v[32:35]
	v_mfma_f32_16x16x32_bf16 v[28:31], v[132:135], v[206:209], v[28:31]
	v_mfma_f32_16x16x32_bf16 v[16:19], v[108:111], v[214:217], v[16:19]
	v_mfma_f32_16x16x32_bf16 v[12:15], v[132:135], v[214:217], v[12:15]
	v_mfma_f32_16x16x32_bf16 v[64:67], v[112:115], v[178:181], v[64:67]
	v_mfma_f32_16x16x32_bf16 v[60:63], v[136:139], v[178:181], v[60:63]
	v_mfma_f32_16x16x32_bf16 v[48:51], v[112:115], v[190:193], v[48:51]
	v_mfma_f32_16x16x32_bf16 v[44:47], v[136:139], v[190:193], v[44:47]
	v_mfma_f32_16x16x32_bf16 v[32:35], v[112:115], v[210:213], v[32:35]
	v_mfma_f32_16x16x32_bf16 v[28:31], v[136:139], v[210:213], v[28:31]
	v_mfma_f32_16x16x32_bf16 v[16:19], v[112:115], v[218:221], v[16:19]
	v_mfma_f32_16x16x32_bf16 v[12:15], v[136:139], v[218:221], v[12:15]
	v_mfma_f32_16x16x32_bf16 v[56:59], v[140:143], v[174:177], v[56:59]
	v_mfma_f32_16x16x32_bf16 v[52:55], v[166:169], v[174:177], v[52:55]
	v_mfma_f32_16x16x32_bf16 v[40:43], v[140:143], v[186:189], v[40:43]
	v_mfma_f32_16x16x32_bf16 v[36:39], v[166:169], v[186:189], v[36:39]
	v_mfma_f32_16x16x32_bf16 v[24:27], v[140:143], v[206:209], v[24:27]
	v_mfma_f32_16x16x32_bf16 v[20:23], v[166:169], v[206:209], v[20:23]
	v_mfma_f32_16x16x32_bf16 v[8:11], v[140:143], v[214:217], v[8:11]
	v_mfma_f32_16x16x32_bf16 v[4:7], v[166:169], v[214:217], v[4:7]
	v_mfma_f32_16x16x32_bf16 v[56:59], v[144:147], v[178:181], v[56:59]
	v_mfma_f32_16x16x32_bf16 v[52:55], v[170:173], v[178:181], v[52:55]
	v_mfma_f32_16x16x32_bf16 v[40:43], v[144:147], v[190:193], v[40:43]
	v_mfma_f32_16x16x32_bf16 v[36:39], v[170:173], v[190:193], v[36:39]
	v_mfma_f32_16x16x32_bf16 v[24:27], v[144:147], v[210:213], v[24:27]
	v_mfma_f32_16x16x32_bf16 v[20:23], v[170:173], v[210:213], v[20:23]
	v_mfma_f32_16x16x32_bf16 v[8:11], v[144:147], v[218:221], v[8:11]
	v_mfma_f32_16x16x32_bf16 v[4:7], v[170:173], v[218:221], v[4:7]
	s_barrier
	s_add_i32 s60, 0, 0x18000
	s_add_i32 s61, 0, 0x1c000
	v_add_u32_e32 v136, s60, v183
	v_add_u32_e32 v170, s61, v183
	ds_read_b128 v[108:111], v136
	ds_read_b128 v[112:115], v136 offset:1024
	ds_read_b128 v[132:135], v136 offset:2048
	ds_read_b128 v[136:139], v136 offset:3072
	ds_read_b128 v[140:143], v170
	ds_read_b128 v[144:147], v170 offset:1024
	ds_read_b128 v[166:169], v170 offset:2048
	ds_read_b128 v[170:173], v170 offset:3072
	s_add_u32 s22, s22, 0x40000
	s_addc_u32 s23, s23, 0
	s_mov_b32 m0, s28
	v_lshl_add_u64 v[242:243], s[22:23], 0, v[160:161]
	ds_read_b128 v[174:177], v184 offset:32768
	ds_read_b128 v[178:181], v184 offset:33792
	ds_read_b128 v[186:189], v184 offset:34816
	ds_read_b128 v[190:193], v184 offset:35840
	ds_read_b128 v[206:209], v184 offset:36864
	ds_read_b128 v[210:213], v184 offset:37888
	ds_read_b128 v[214:217], v184 offset:38912
	ds_read_b128 v[218:221], v184 offset:39936
	global_load_lds_dwordx4 v[242:243], off
	v_lshl_add_u64 v[242:243], s[22:23], 0, v[158:159]
	s_mov_b32 m0, s29
	s_nop 0
	global_load_lds_dwordx4 v[242:243], off
	s_waitcnt vmcnt(8)
	s_waitcnt lgkmcnt(0)
	s_barrier
	s_waitcnt lgkmcnt(0)
	v_mfma_f32_16x16x32_bf16 v[152:155], v[108:111], v[174:177], v[152:155]
	v_mfma_f32_16x16x32_bf16 v[148:151], v[132:135], v[174:177], v[148:151]
	v_mfma_f32_16x16x32_bf16 v[128:131], v[108:111], v[186:189], v[128:131]
	v_mfma_f32_16x16x32_bf16 v[124:127], v[132:135], v[186:189], v[124:127]
	v_mfma_f32_16x16x32_bf16 v[96:99], v[108:111], v[206:209], v[96:99]
	v_mfma_f32_16x16x32_bf16 v[92:95], v[132:135], v[206:209], v[92:95]
	v_mfma_f32_16x16x32_bf16 v[80:83], v[108:111], v[214:217], v[80:83]
	v_mfma_f32_16x16x32_bf16 v[76:79], v[132:135], v[214:217], v[76:79]
	v_mfma_f32_16x16x32_bf16 v[152:155], v[112:115], v[178:181], v[152:155]
	v_mfma_f32_16x16x32_bf16 v[148:151], v[136:139], v[178:181], v[148:151]
	v_mfma_f32_16x16x32_bf16 v[128:131], v[112:115], v[190:193], v[128:131]
	v_mfma_f32_16x16x32_bf16 v[124:127], v[136:139], v[190:193], v[124:127]
	v_mfma_f32_16x16x32_bf16 v[96:99], v[112:115], v[210:213], v[96:99]
	v_mfma_f32_16x16x32_bf16 v[92:95], v[136:139], v[210:213], v[92:95]
	v_mfma_f32_16x16x32_bf16 v[80:83], v[112:115], v[218:221], v[80:83]
	v_mfma_f32_16x16x32_bf16 v[76:79], v[136:139], v[218:221], v[76:79]
	v_mfma_f32_16x16x32_bf16 v[104:107], v[140:143], v[174:177], v[104:107]
	v_mfma_f32_16x16x32_bf16 v[100:103], v[166:169], v[174:177], v[100:103]
	v_mfma_f32_16x16x32_bf16 v[120:123], v[140:143], v[186:189], v[120:123]
	v_mfma_f32_16x16x32_bf16 v[116:119], v[166:169], v[186:189], v[116:119]
	v_mfma_f32_16x16x32_bf16 v[88:91], v[140:143], v[206:209], v[88:91]
	v_mfma_f32_16x16x32_bf16 v[84:87], v[166:169], v[206:209], v[84:87]
	v_mfma_f32_16x16x32_bf16 v[72:75], v[140:143], v[214:217], v[72:75]
	v_mfma_f32_16x16x32_bf16 v[68:71], v[166:169], v[214:217], v[68:71]
	v_mfma_f32_16x16x32_bf16 v[104:107], v[144:147], v[178:181], v[104:107]
	v_mfma_f32_16x16x32_bf16 v[100:103], v[170:173], v[178:181], v[100:103]
	v_mfma_f32_16x16x32_bf16 v[120:123], v[144:147], v[190:193], v[120:123]
	v_mfma_f32_16x16x32_bf16 v[116:119], v[170:173], v[190:193], v[116:119]
	v_mfma_f32_16x16x32_bf16 v[88:91], v[144:147], v[210:213], v[88:91]
	v_mfma_f32_16x16x32_bf16 v[84:87], v[170:173], v[210:213], v[84:87]
	v_mfma_f32_16x16x32_bf16 v[72:75], v[144:147], v[218:221], v[72:75]
	v_mfma_f32_16x16x32_bf16 v[68:71], v[170:173], v[218:221], v[68:71]
	s_barrier
	s_add_i32 s22, s60, s25
	v_lshl_add_u64 v[194:195], v[194:195], 0, s[96:97]
	s_mov_b32 m0, s22
	ds_read_b128 v[174:177], v184 offset:49152
	ds_read_b128 v[178:181], v184 offset:50176
	ds_read_b128 v[186:189], v184 offset:51200
	ds_read_b128 v[190:193], v184 offset:52224
	ds_read_b128 v[206:209], v184 offset:53248
	ds_read_b128 v[210:213], v184 offset:54272
	ds_read_b128 v[214:217], v184 offset:55296
	ds_read_b128 v[218:221], v184 offset:56320
	global_load_lds_dwordx4 v[194:195], off
	s_add_i32 m0, s22, 0x2000
	s_add_u32 s20, s20, 0x40080
	v_lshl_add_u64 v[194:195], v[236:237], 0, s[96:97]
	s_addc_u32 s21, s21, 0
	s_add_i32 s22, s61, s25
	global_load_lds_dwordx4 v[194:195], off
	v_lshl_add_u64 v[194:195], s[20:21], 0, v[2:3]
	s_mov_b32 m0, s22
	s_nop 0
	global_load_lds_dwordx4 v[194:195], off
	v_lshl_add_u64 v[194:195], s[20:21], 0, v[156:157]
	s_add_i32 m0, s22, 0x2000
	s_nop 0
	global_load_lds_dwordx4 v[194:195], off
	v_lshl_add_u64 v[194:195], v[238:239], 0, s[96:97]
	s_mov_b32 m0, s34
	s_nop 0
	global_load_lds_dwordx4 v[194:195], off
	v_lshl_add_u64 v[194:195], v[240:241], 0, s[96:97]
	s_mov_b32 m0, s35
	s_nop 0
	global_load_lds_dwordx4 v[194:195], off
	s_waitcnt vmcnt(8)
	s_waitcnt lgkmcnt(0)
	s_barrier
	s_waitcnt lgkmcnt(0)
	v_mfma_f32_16x16x32_bf16 v[64:67], v[108:111], v[174:177], v[64:67]
	v_mfma_f32_16x16x32_bf16 v[60:63], v[132:135], v[174:177], v[60:63]
	v_mfma_f32_16x16x32_bf16 v[48:51], v[108:111], v[186:189], v[48:51]
	v_mfma_f32_16x16x32_bf16 v[44:47], v[132:135], v[186:189], v[44:47]
	v_mfma_f32_16x16x32_bf16 v[32:35], v[108:111], v[206:209], v[32:35]
	v_mfma_f32_16x16x32_bf16 v[28:31], v[132:135], v[206:209], v[28:31]
	v_mfma_f32_16x16x32_bf16 v[16:19], v[108:111], v[214:217], v[16:19]
	v_mfma_f32_16x16x32_bf16 v[12:15], v[132:135], v[214:217], v[12:15]
	v_mfma_f32_16x16x32_bf16 v[64:67], v[112:115], v[178:181], v[64:67]
	v_mfma_f32_16x16x32_bf16 v[60:63], v[136:139], v[178:181], v[60:63]
	v_mfma_f32_16x16x32_bf16 v[48:51], v[112:115], v[190:193], v[48:51]
	v_mfma_f32_16x16x32_bf16 v[44:47], v[136:139], v[190:193], v[44:47]
	v_mfma_f32_16x16x32_bf16 v[32:35], v[112:115], v[210:213], v[32:35]
	v_mfma_f32_16x16x32_bf16 v[28:31], v[136:139], v[210:213], v[28:31]
	v_mfma_f32_16x16x32_bf16 v[16:19], v[112:115], v[218:221], v[16:19]
	v_mfma_f32_16x16x32_bf16 v[12:15], v[136:139], v[218:221], v[12:15]
	v_mfma_f32_16x16x32_bf16 v[56:59], v[140:143], v[174:177], v[56:59]
	v_mfma_f32_16x16x32_bf16 v[52:55], v[166:169], v[174:177], v[52:55]
	v_mfma_f32_16x16x32_bf16 v[40:43], v[140:143], v[186:189], v[40:43]
	v_mfma_f32_16x16x32_bf16 v[36:39], v[166:169], v[186:189], v[36:39]
	v_mfma_f32_16x16x32_bf16 v[24:27], v[140:143], v[206:209], v[24:27]
	v_mfma_f32_16x16x32_bf16 v[20:23], v[166:169], v[206:209], v[20:23]
	v_mfma_f32_16x16x32_bf16 v[8:11], v[140:143], v[214:217], v[8:11]
	v_mfma_f32_16x16x32_bf16 v[4:7], v[166:169], v[214:217], v[4:7]
	v_mfma_f32_16x16x32_bf16 v[56:59], v[144:147], v[178:181], v[56:59]
	v_mfma_f32_16x16x32_bf16 v[52:55], v[170:173], v[178:181], v[52:55]
	v_mfma_f32_16x16x32_bf16 v[40:43], v[144:147], v[190:193], v[40:43]
	v_mfma_f32_16x16x32_bf16 v[36:39], v[170:173], v[190:193], v[36:39]
	v_mfma_f32_16x16x32_bf16 v[24:27], v[144:147], v[210:213], v[24:27]
	v_mfma_f32_16x16x32_bf16 v[20:23], v[170:173], v[210:213], v[20:23]
	v_mfma_f32_16x16x32_bf16 v[8:11], v[144:147], v[218:221], v[8:11]
	v_mfma_f32_16x16x32_bf16 v[4:7], v[170:173], v[218:221], v[4:7]
	s_barrier
	s_add_i32 s59, s59, 2
	s_add_u32 s18, s18, 0x100
	s_addc_u32 s19, s19, 0
	s_add_u32 s57, s57, 0x100
	s_addc_u32 s58, s58, 0
	s_cmp_gt_u32 s59, 13
	s_cbranch_scc0 .LBB0_340
	v_mov_b32_e32 v169, v1
	v_mov_b32_e32 v109, v182
	s_lshl_b32 s18, s42, 8
	s_lshl_b32 s19, s55, 8
	s_add_i32 s18, s18, s30
	s_or_b32 s19, s19, s31
	v_lshl_add_u32 v170, v169, 4, v109
	v_add_u32_e32 v174, s18, v109
	v_lshl_add_u32 v108, v169, 3, s19
	v_and_b32_e32 v166, 3, v109
	v_and_b32_e32 v109, -4, v170
	v_lshl_add_u32 v185, v166, 6, v109
	v_ashrrev_i32_e32 v109, 31, v108
	v_ashrrev_i32_e32 v175, 31, v174
	v_lshl_add_u64 v[176:177], v[108:109], 1, s[48:49]
	v_lshlrev_b64 v[108:109], 11, v[174:175]
	v_lshl_add_u64 v[108:109], v[176:177], 0, v[108:109]
	global_load_dwordx4 v[188:191], v[108:109], off
	global_load_dwordx4 v[192:195], v[108:109], off offset:256
	v_add_u32_e32 v180, 16, v174
	v_ashrrev_i32_e32 v181, 31, v180
	v_lshlrev_b64 v[108:109], 11, v[180:181]
	v_add_u32_e32 v178, 32, v174
	v_lshl_add_u64 v[108:109], v[176:177], 0, v[108:109]
	v_ashrrev_i32_e32 v179, 31, v178
	global_load_dwordx4 v[144:147], v[108:109], off
	global_load_dwordx4 v[140:143], v[108:109], off offset:256
	v_lshlrev_b64 v[108:109], 11, v[178:179]
	v_add_u32_e32 v172, 48, v174
	v_ashrrev_i32_e32 v167, 2, v170
	v_lshlrev_b32_e32 v170, 2, v170
	v_lshl_add_u64 v[108:109], v[176:177], 0, v[108:109]
	v_ashrrev_i32_e32 v173, 31, v172
	v_xor_b32_e32 v187, 64, v170
	v_xor_b32_e32 v186, 0x80, v170
	v_add_u32_e32 v170, 0x80, v174
	global_load_dwordx4 v[136:139], v[108:109], off
	global_load_dwordx4 v[132:135], v[108:109], off offset:256
	v_lshlrev_b64 v[108:109], 11, v[172:173]
	v_ashrrev_i32_e32 v171, 31, v170
	v_lshl_add_u64 v[108:109], v[176:177], 0, v[108:109]
	global_load_dwordx4 v[112:115], v[108:109], off
	s_nop 0
	global_load_dwordx4 v[108:111], v[108:109], off offset:256
	v_add_u32_e32 v168, s18, v167
	s_lshl_b32 s18, s55, 2
	v_lshl_or_b32 v166, v166, 3, s19
	s_ashr_i32 s19, s18, 31
	v_ashrrev_i32_e32 v167, 31, v166
	v_cmp_eq_u32_e64 s[42:43], 0, v169
	s_lshl_b64 s[18:19], s[18:19], 2
	v_ashrrev_i32_e32 v169, 31, v168
	v_lshl_add_u64 v[166:167], v[166:167], 1, s[48:49]
	s_add_u32 s18, s36, s18
	s_addc_u32 s19, s37, s19
	s_waitcnt vmcnt(0)
	v_lshlrev_b32_e32 v208, 16, v190
	v_and_b32_e32 v209, 0xffff0000, v190
	v_lshlrev_b32_e32 v206, 16, v188
	v_and_b32_e32 v207, 0xffff0000, v188
	v_lshlrev_b32_e32 v188, 16, v189
	v_and_b32_e32 v189, 0xffff0000, v189
	v_lshlrev_b32_e32 v190, 16, v191
	v_and_b32_e32 v191, 0xffff0000, v191
	v_pk_add_f32 v[148:149], v[148:149], v[208:209]
	v_pk_add_f32 v[188:189], v[154:155], v[188:189]
	v_pk_add_f32 v[206:207], v[152:153], v[206:207]
	v_pk_add_f32 v[190:191], v[150:151], v[190:191]
	v_cvt_pk_bf16_f32 v153, v148, v149
	v_mul_f32_e32 v149, v149, v149
	v_mul_f32_e32 v150, v207, v207
	v_mul_f32_e32 v155, v189, v189
	v_fmac_f32_e32 v149, v148, v148
	v_mul_f32_e32 v148, v191, v191
	v_fmac_f32_e32 v150, v206, v206
	v_fmac_f32_e32 v155, v188, v188
	v_fmac_f32_e32 v148, v190, v190
	v_add_f32_e32 v150, v150, v155
	v_add_f32_e32 v148, v149, v148
	v_cvt_pk_bf16_f32 v154, v190, v191
	v_add_f32_e32 v150, v150, v148
	v_lshlrev_b32_e32 v148, 16, v192
	v_and_b32_e32 v149, 0xffff0000, v192
	v_lshlrev_b32_e32 v190, 16, v194
	v_and_b32_e32 v191, 0xffff0000, v194
	v_cvt_pk_bf16_f32 v152, v188, v189
	v_lshlrev_b32_e32 v188, 16, v193
	v_and_b32_e32 v189, 0xffff0000, v193
	v_lshlrev_b32_e32 v192, 16, v195
	v_and_b32_e32 v193, 0xffff0000, v195
	v_pk_add_f32 v[104:105], v[104:105], v[148:149]
	v_pk_add_f32 v[100:101], v[100:101], v[190:191]
	v_pk_add_f32 v[106:107], v[106:107], v[188:189]
	v_pk_add_f32 v[102:103], v[102:103], v[192:193]
	v_cvt_pk_bf16_f32 v155, v104, v105
	v_cvt_pk_bf16_f32 v189, v100, v101
	v_mul_f32_e32 v105, v105, v105
	v_mul_f32_e32 v101, v101, v101
	v_fmac_f32_e32 v105, v104, v104
	v_mul_f32_e32 v104, v107, v107
	v_fmac_f32_e32 v101, v100, v100
	v_mul_f32_e32 v100, v103, v103
	v_fmac_f32_e32 v104, v106, v106
	v_fmac_f32_e32 v100, v102, v102
	v_add_f32_e32 v104, v105, v104
	v_add_f32_e32 v100, v101, v100
	v_add_f32_e32 v100, v104, v100
	v_add_f32_e32 v150, v150, v100
	v_lshlrev_b64 v[100:101], 11, v[170:171]
	v_lshl_add_u64 v[100:101], v[176:177], 0, v[100:101]
	v_cvt_pk_bf16_f32 v188, v106, v107
	v_cvt_pk_bf16_f32 v190, v102, v103
	global_load_dwordx4 v[104:107], v[100:101], off
	s_nop 0
	global_load_dwordx4 v[100:103], v[100:101], off offset:256
	v_cvt_pk_bf16_f32 v151, v206, v207
	ds_bpermute_b32 v192, v185, v151
	ds_bpermute_b32 v151, v187, v150
	ds_bpermute_b32 v193, v185, v152
	ds_bpermute_b32 v194, v185, v153
	ds_bpermute_b32 v195, v185, v154
	ds_bpermute_b32 v152, v185, v155
	s_waitcnt lgkmcnt(4)
	v_add_f32_e32 v150, v150, v151
	ds_bpermute_b32 v153, v185, v188
	ds_bpermute_b32 v154, v185, v189
	ds_bpermute_b32 v155, v185, v190
	ds_bpermute_b32 v151, v186, v150
	v_lshlrev_b64 v[148:149], 11, v[168:169]
	v_lshl_add_u64 v[148:149], v[166:167], 0, v[148:149]
	s_waitcnt lgkmcnt(5)
	global_store_dwordx4 v[148:149], v[192:195], off
	s_waitcnt lgkmcnt(1)
	global_store_dwordx4 v[148:149], v[152:155], off offset:256
	s_and_saveexec_b64 s[20:21], s[42:43]
	s_cbranch_execz .LBB0_343
	s_waitcnt lgkmcnt(0)
	v_add_f32_e32 v152, v150, v151
	v_lshlrev_b64 v[150:151], 6, v[174:175]
	v_lshl_add_u64 v[150:151], s[18:19], 0, v[150:151]
	global_store_dword v[150:151], v152, off

.LBB0_395:
	s_add_u32 s18, s84, s72
	s_addc_u32 s19, s85, s73
	s_add_u32 s89, s86, s72
	s_addc_u32 s90, s87, s73
	s_add_i32 s91, 0, 0x10000
	s_cmpk_eq_i32 s72, 0xb00
	s_cselect_b32 s21, s41, s19
	s_cselect_b32 s20, s40, s18
	s_cselect_b32 s19, s51, s90
	s_cselect_b32 s18, s50, s89
	s_add_i32 s89, 0, 0x14000
	v_add_u32_e32 v144, s91, v236
	v_add_u32_e32 v160, s89, v236
	ds_read_b128 v[132:135], v144
	ds_read_b128 v[136:139], v144 offset:1024
	ds_read_b128 v[140:143], v144 offset:2048
	ds_read_b128 v[144:147], v144 offset:3072
	ds_read_b128 v[148:151], v160
	ds_read_b128 v[152:155], v160 offset:1024
	ds_read_b128 v[156:159], v160 offset:2048
	ds_read_b128 v[160:163], v160 offset:3072
	v_lshl_add_u64 v[220:221], v[216:217], 0, s[72:73]
	s_add_i32 m0, s28, 0xc000
	ds_read_b128 v[164:167], v237
	ds_read_b128 v[168:171], v237 offset:1024
	ds_read_b128 v[172:175], v237 offset:2048
	ds_read_b128 v[176:179], v237 offset:3072
	ds_read_b128 v[180:183], v237 offset:4096
	ds_read_b128 v[184:187], v237 offset:5120
	ds_read_b128 v[188:191], v237 offset:6144
	ds_read_b128 v[192:195], v237 offset:7168
	global_load_lds_dwordx4 v[220:221], off
	v_lshl_add_u64 v[220:221], v[218:219], 0, s[72:73]
	s_add_i32 m0, s28, 0xe000
	s_nop 0
	global_load_lds_dwordx4 v[220:221], off
	s_waitcnt vmcnt(8)
	s_waitcnt lgkmcnt(0)
	s_barrier
	s_waitcnt lgkmcnt(0)
	v_mfma_f32_16x16x32_bf16 v[128:131], v[132:135], v[164:167], v[128:131]
	v_mfma_f32_16x16x32_bf16 v[124:127], v[140:143], v[164:167], v[124:127]
	v_mfma_f32_16x16x32_bf16 v[112:115], v[132:135], v[172:175], v[112:115]
	v_mfma_f32_16x16x32_bf16 v[108:111], v[140:143], v[172:175], v[108:111]
	v_mfma_f32_16x16x32_bf16 v[96:99], v[132:135], v[180:183], v[96:99]
	v_mfma_f32_16x16x32_bf16 v[92:95], v[140:143], v[180:183], v[92:95]
	v_mfma_f32_16x16x32_bf16 v[80:83], v[132:135], v[188:191], v[80:83]
	v_mfma_f32_16x16x32_bf16 v[76:79], v[140:143], v[188:191], v[76:79]
	v_mfma_f32_16x16x32_bf16 v[128:131], v[136:139], v[168:171], v[128:131]
	v_mfma_f32_16x16x32_bf16 v[124:127], v[144:147], v[168:171], v[124:127]
	v_mfma_f32_16x16x32_bf16 v[112:115], v[136:139], v[176:179], v[112:115]
	v_mfma_f32_16x16x32_bf16 v[108:111], v[144:147], v[176:179], v[108:111]
	v_mfma_f32_16x16x32_bf16 v[96:99], v[136:139], v[184:187], v[96:99]
	v_mfma_f32_16x16x32_bf16 v[92:95], v[144:147], v[184:187], v[92:95]
	v_mfma_f32_16x16x32_bf16 v[80:83], v[136:139], v[192:195], v[80:83]
	v_mfma_f32_16x16x32_bf16 v[76:79], v[144:147], v[192:195], v[76:79]
	v_mfma_f32_16x16x32_bf16 v[120:123], v[148:151], v[164:167], v[120:123]
	v_mfma_f32_16x16x32_bf16 v[116:119], v[156:159], v[164:167], v[116:119]
	v_mfma_f32_16x16x32_bf16 v[104:107], v[148:151], v[172:175], v[104:107]
	v_mfma_f32_16x16x32_bf16 v[100:103], v[156:159], v[172:175], v[100:103]
	v_mfma_f32_16x16x32_bf16 v[88:91], v[148:151], v[180:183], v[88:91]
	v_mfma_f32_16x16x32_bf16 v[84:87], v[156:159], v[180:183], v[84:87]
	v_mfma_f32_16x16x32_bf16 v[72:75], v[148:151], v[188:191], v[72:75]
	v_mfma_f32_16x16x32_bf16 v[68:71], v[156:159], v[188:191], v[68:71]
	v_mfma_f32_16x16x32_bf16 v[120:123], v[152:155], v[168:171], v[120:123]
	v_mfma_f32_16x16x32_bf16 v[116:119], v[160:163], v[168:171], v[116:119]
	v_mfma_f32_16x16x32_bf16 v[104:107], v[152:155], v[176:179], v[104:107]
	v_mfma_f32_16x16x32_bf16 v[100:103], v[160:163], v[176:179], v[100:103]
	v_mfma_f32_16x16x32_bf16 v[88:91], v[152:155], v[184:187], v[88:91]
	v_mfma_f32_16x16x32_bf16 v[84:87], v[160:163], v[184:187], v[84:87]
	v_mfma_f32_16x16x32_bf16 v[72:75], v[152:155], v[192:195], v[72:75]
	v_mfma_f32_16x16x32_bf16 v[68:71], v[160:163], v[192:195], v[68:71]
	s_barrier
	s_add_i32 s90, s91, s27
	v_lshl_add_u64 v[220:221], s[18:19], 0, v[2:3]
	s_mov_b32 m0, s90
	ds_read_b128 v[164:167], v237 offset:16384
	ds_read_b128 v[168:171], v237 offset:17408
	ds_read_b128 v[172:175], v237 offset:18432
	ds_read_b128 v[176:179], v237 offset:19456
	ds_read_b128 v[180:183], v237 offset:20480
	ds_read_b128 v[184:187], v237 offset:21504
	ds_read_b128 v[188:191], v237 offset:22528
	ds_read_b128 v[192:195], v237 offset:23552
	global_load_lds_dwordx4 v[220:221], off
	s_add_i32 m0, s90, 0x2000
	s_add_u32 s90, s18, 0x60000
	v_lshl_add_u64 v[238:239], s[18:19], 0, v[206:207]
	s_addc_u32 s91, s19, 0
	s_add_i32 s89, s89, s27
	global_load_lds_dwordx4 v[238:239], off
	v_lshl_add_u64 v[240:241], s[90:91], 0, v[2:3]
	s_mov_b32 m0, s89
	v_lshl_add_u64 v[242:243], s[20:21], 0, v[208:209]
	global_load_lds_dwordx4 v[240:241], off
	v_lshl_add_u64 v[240:241], s[90:91], 0, v[206:207]
	s_add_i32 m0, s89, 0x2000
	s_nop 0
	global_load_lds_dwordx4 v[240:241], off
	v_lshl_add_u64 v[240:241], s[20:21], 0, v[210:211]
	s_mov_b32 m0, s28
	s_nop 0
	global_load_lds_dwordx4 v[240:241], off
	s_mov_b32 m0, s29
	s_nop 0
	global_load_lds_dwordx4 v[242:243], off
	s_waitcnt vmcnt(8)
	s_waitcnt lgkmcnt(0)
	s_barrier
	s_waitcnt lgkmcnt(0)
	v_mfma_f32_16x16x32_bf16 v[52:55], v[132:135], v[164:167], v[52:55]
	v_mfma_f32_16x16x32_bf16 v[60:63], v[140:143], v[164:167], v[60:63]
	v_mfma_f32_16x16x32_bf16 v[36:39], v[132:135], v[172:175], v[36:39]
	v_mfma_f32_16x16x32_bf16 v[44:47], v[140:143], v[172:175], v[44:47]
	v_mfma_f32_16x16x32_bf16 v[20:23], v[132:135], v[180:183], v[20:23]
	v_mfma_f32_16x16x32_bf16 v[28:31], v[140:143], v[180:183], v[28:31]
	v_mfma_f32_16x16x32_bf16 v[4:7], v[132:135], v[188:191], v[4:7]
	v_mfma_f32_16x16x32_bf16 v[16:19], v[140:143], v[188:191], v[16:19]
	v_mfma_f32_16x16x32_bf16 v[52:55], v[136:139], v[168:171], v[52:55]
	v_mfma_f32_16x16x32_bf16 v[60:63], v[144:147], v[168:171], v[60:63]
	v_mfma_f32_16x16x32_bf16 v[36:39], v[136:139], v[176:179], v[36:39]
	v_mfma_f32_16x16x32_bf16 v[44:47], v[144:147], v[176:179], v[44:47]
	v_mfma_f32_16x16x32_bf16 v[20:23], v[136:139], v[184:187], v[20:23]
	v_mfma_f32_16x16x32_bf16 v[28:31], v[144:147], v[184:187], v[28:31]
	v_mfma_f32_16x16x32_bf16 v[4:7], v[136:139], v[192:195], v[4:7]
	v_mfma_f32_16x16x32_bf16 v[16:19], v[144:147], v[192:195], v[16:19]
	v_mfma_f32_16x16x32_bf16 v[56:59], v[148:151], v[164:167], v[56:59]
	v_mfma_f32_16x16x32_bf16 v[64:67], v[156:159], v[164:167], v[64:67]
	v_mfma_f32_16x16x32_bf16 v[40:43], v[148:151], v[172:175], v[40:43]
	v_mfma_f32_16x16x32_bf16 v[48:51], v[156:159], v[172:175], v[48:51]
	v_mfma_f32_16x16x32_bf16 v[24:27], v[148:151], v[180:183], v[24:27]
	v_mfma_f32_16x16x32_bf16 v[32:35], v[156:159], v[180:183], v[32:35]
	v_mfma_f32_16x16x32_bf16 v[8:11], v[148:151], v[188:191], v[8:11]
	v_mfma_f32_16x16x32_bf16 v[12:15], v[156:159], v[188:191], v[12:15]
	v_mfma_f32_16x16x32_bf16 v[56:59], v[152:155], v[168:171], v[56:59]
	v_mfma_f32_16x16x32_bf16 v[64:67], v[160:163], v[168:171], v[64:67]
	v_mfma_f32_16x16x32_bf16 v[40:43], v[152:155], v[176:179], v[40:43]
	v_mfma_f32_16x16x32_bf16 v[48:51], v[160:163], v[176:179], v[48:51]
	v_mfma_f32_16x16x32_bf16 v[24:27], v[152:155], v[184:187], v[24:27]
	v_mfma_f32_16x16x32_bf16 v[32:35], v[160:163], v[184:187], v[32:35]
	v_mfma_f32_16x16x32_bf16 v[8:11], v[152:155], v[192:195], v[8:11]
	v_mfma_f32_16x16x32_bf16 v[12:15], v[160:163], v[192:195], v[12:15]
	s_barrier
	s_add_i32 s89, 0, 0x18000
	s_add_i32 s90, 0, 0x1c000
	v_add_u32_e32 v144, s89, v236
	v_add_u32_e32 v160, s90, v236
	ds_read_b128 v[132:135], v144
	ds_read_b128 v[136:139], v144 offset:1024
	ds_read_b128 v[140:143], v144 offset:2048
	ds_read_b128 v[144:147], v144 offset:3072
	ds_read_b128 v[148:151], v160
	ds_read_b128 v[152:155], v160 offset:1024
	ds_read_b128 v[156:159], v160 offset:2048
	ds_read_b128 v[160:163], v160 offset:3072
	s_add_u32 s20, s20, 0x60000
	s_addc_u32 s21, s21, 0
	s_mov_b32 m0, s30
	v_lshl_add_u64 v[244:245], s[20:21], 0, v[210:211]
	ds_read_b128 v[164:167], v237 offset:32768
	ds_read_b128 v[168:171], v237 offset:33792
	ds_read_b128 v[172:175], v237 offset:34816
	ds_read_b128 v[176:179], v237 offset:35840
	ds_read_b128 v[180:183], v237 offset:36864
	ds_read_b128 v[184:187], v237 offset:37888
	ds_read_b128 v[188:191], v237 offset:38912
	ds_read_b128 v[192:195], v237 offset:39936
	global_load_lds_dwordx4 v[244:245], off
	v_lshl_add_u64 v[244:245], s[20:21], 0, v[208:209]
	s_mov_b32 m0, s31
	s_nop 0
	global_load_lds_dwordx4 v[244:245], off
	s_waitcnt vmcnt(8)
	s_waitcnt lgkmcnt(0)
	s_barrier
	s_waitcnt lgkmcnt(0)
	v_mfma_f32_16x16x32_bf16 v[128:131], v[132:135], v[164:167], v[128:131]
	v_mfma_f32_16x16x32_bf16 v[124:127], v[140:143], v[164:167], v[124:127]
	v_mfma_f32_16x16x32_bf16 v[112:115], v[132:135], v[172:175], v[112:115]
	v_mfma_f32_16x16x32_bf16 v[108:111], v[140:143], v[172:175], v[108:111]
	v_mfma_f32_16x16x32_bf16 v[96:99], v[132:135], v[180:183], v[96:99]
	v_mfma_f32_16x16x32_bf16 v[92:95], v[140:143], v[180:183], v[92:95]
	v_mfma_f32_16x16x32_bf16 v[80:83], v[132:135], v[188:191], v[80:83]
	v_mfma_f32_16x16x32_bf16 v[76:79], v[140:143], v[188:191], v[76:79]
	v_mfma_f32_16x16x32_bf16 v[128:131], v[136:139], v[168:171], v[128:131]
	v_mfma_f32_16x16x32_bf16 v[124:127], v[144:147], v[168:171], v[124:127]
	v_mfma_f32_16x16x32_bf16 v[112:115], v[136:139], v[176:179], v[112:115]
	v_mfma_f32_16x16x32_bf16 v[108:111], v[144:147], v[176:179], v[108:111]
	v_mfma_f32_16x16x32_bf16 v[96:99], v[136:139], v[184:187], v[96:99]
	v_mfma_f32_16x16x32_bf16 v[92:95], v[144:147], v[184:187], v[92:95]
	v_mfma_f32_16x16x32_bf16 v[80:83], v[136:139], v[192:195], v[80:83]
	v_mfma_f32_16x16x32_bf16 v[76:79], v[144:147], v[192:195], v[76:79]
	v_mfma_f32_16x16x32_bf16 v[120:123], v[148:151], v[164:167], v[120:123]
	v_mfma_f32_16x16x32_bf16 v[116:119], v[156:159], v[164:167], v[116:119]
	v_mfma_f32_16x16x32_bf16 v[104:107], v[148:151], v[172:175], v[104:107]
	v_mfma_f32_16x16x32_bf16 v[100:103], v[156:159], v[172:175], v[100:103]
	v_mfma_f32_16x16x32_bf16 v[88:91], v[148:151], v[180:183], v[88:91]
	v_mfma_f32_16x16x32_bf16 v[84:87], v[156:159], v[180:183], v[84:87]
	v_mfma_f32_16x16x32_bf16 v[72:75], v[148:151], v[188:191], v[72:75]
	v_mfma_f32_16x16x32_bf16 v[68:71], v[156:159], v[188:191], v[68:71]
	v_mfma_f32_16x16x32_bf16 v[120:123], v[152:155], v[168:171], v[120:123]
	v_mfma_f32_16x16x32_bf16 v[116:119], v[160:163], v[168:171], v[116:119]
	v_mfma_f32_16x16x32_bf16 v[104:107], v[152:155], v[176:179], v[104:107]
	v_mfma_f32_16x16x32_bf16 v[100:103], v[160:163], v[176:179], v[100:103]
	v_mfma_f32_16x16x32_bf16 v[88:91], v[152:155], v[184:187], v[88:91]
	v_mfma_f32_16x16x32_bf16 v[84:87], v[160:163], v[184:187], v[84:87]
	v_mfma_f32_16x16x32_bf16 v[72:75], v[152:155], v[192:195], v[72:75]
	v_mfma_f32_16x16x32_bf16 v[68:71], v[160:163], v[192:195], v[68:71]
	s_barrier
	s_add_i32 s20, s89, s27
	v_lshl_add_u64 v[220:221], v[220:221], 0, s[96:97]
	s_mov_b32 m0, s20
	ds_read_b128 v[164:167], v237 offset:49152
	ds_read_b128 v[168:171], v237 offset:50176
	ds_read_b128 v[172:175], v237 offset:51200
	ds_read_b128 v[176:179], v237 offset:52224
	ds_read_b128 v[180:183], v237 offset:53248
	ds_read_b128 v[184:187], v237 offset:54272
	ds_read_b128 v[188:191], v237 offset:55296
	ds_read_b128 v[192:195], v237 offset:56320
	global_load_lds_dwordx4 v[220:221], off
	s_add_i32 m0, s20, 0x2000
	s_add_u32 s18, s18, 0x60080
	v_lshl_add_u64 v[220:221], v[238:239], 0, s[96:97]
	s_addc_u32 s19, s19, 0
	s_add_i32 s20, s90, s27
	global_load_lds_dwordx4 v[220:221], off
	v_lshl_add_u64 v[220:221], s[18:19], 0, v[2:3]
	s_mov_b32 m0, s20
	s_nop 0
	global_load_lds_dwordx4 v[220:221], off
	v_lshl_add_u64 v[220:221], s[18:19], 0, v[206:207]
	s_add_i32 m0, s20, 0x2000
	s_nop 0
	global_load_lds_dwordx4 v[220:221], off
	v_lshl_add_u64 v[220:221], v[240:241], 0, s[96:97]
	s_mov_b32 m0, s36
	s_nop 0
	global_load_lds_dwordx4 v[220:221], off
	v_lshl_add_u64 v[220:221], v[242:243], 0, s[96:97]
	s_mov_b32 m0, s37
	s_nop 0
	global_load_lds_dwordx4 v[220:221], off
	s_waitcnt vmcnt(8)
	s_waitcnt lgkmcnt(0)
	s_barrier
	s_waitcnt lgkmcnt(0)
	v_mfma_f32_16x16x32_bf16 v[52:55], v[132:135], v[164:167], v[52:55]
	v_mfma_f32_16x16x32_bf16 v[60:63], v[140:143], v[164:167], v[60:63]
	v_mfma_f32_16x16x32_bf16 v[36:39], v[132:135], v[172:175], v[36:39]
	v_mfma_f32_16x16x32_bf16 v[44:47], v[140:143], v[172:175], v[44:47]
	v_mfma_f32_16x16x32_bf16 v[20:23], v[132:135], v[180:183], v[20:23]
	v_mfma_f32_16x16x32_bf16 v[28:31], v[140:143], v[180:183], v[28:31]
	v_mfma_f32_16x16x32_bf16 v[4:7], v[132:135], v[188:191], v[4:7]
	v_mfma_f32_16x16x32_bf16 v[16:19], v[140:143], v[188:191], v[16:19]
	v_mfma_f32_16x16x32_bf16 v[52:55], v[136:139], v[168:171], v[52:55]
	v_mfma_f32_16x16x32_bf16 v[60:63], v[144:147], v[168:171], v[60:63]
	v_mfma_f32_16x16x32_bf16 v[36:39], v[136:139], v[176:179], v[36:39]
	v_mfma_f32_16x16x32_bf16 v[44:47], v[144:147], v[176:179], v[44:47]
	v_mfma_f32_16x16x32_bf16 v[20:23], v[136:139], v[184:187], v[20:23]
	v_mfma_f32_16x16x32_bf16 v[28:31], v[144:147], v[184:187], v[28:31]
	v_mfma_f32_16x16x32_bf16 v[4:7], v[136:139], v[192:195], v[4:7]
	v_mfma_f32_16x16x32_bf16 v[16:19], v[144:147], v[192:195], v[16:19]
	v_mfma_f32_16x16x32_bf16 v[56:59], v[148:151], v[164:167], v[56:59]
	v_mfma_f32_16x16x32_bf16 v[64:67], v[156:159], v[164:167], v[64:67]
	v_mfma_f32_16x16x32_bf16 v[40:43], v[148:151], v[172:175], v[40:43]
	v_mfma_f32_16x16x32_bf16 v[48:51], v[156:159], v[172:175], v[48:51]
	v_mfma_f32_16x16x32_bf16 v[24:27], v[148:151], v[180:183], v[24:27]
	v_mfma_f32_16x16x32_bf16 v[32:35], v[156:159], v[180:183], v[32:35]
	v_mfma_f32_16x16x32_bf16 v[8:11], v[148:151], v[188:191], v[8:11]
	v_mfma_f32_16x16x32_bf16 v[12:15], v[156:159], v[188:191], v[12:15]
	v_mfma_f32_16x16x32_bf16 v[56:59], v[152:155], v[168:171], v[56:59]
	v_mfma_f32_16x16x32_bf16 v[64:67], v[160:163], v[168:171], v[64:67]
	v_mfma_f32_16x16x32_bf16 v[40:43], v[152:155], v[176:179], v[40:43]
	v_mfma_f32_16x16x32_bf16 v[48:51], v[160:163], v[176:179], v[48:51]
	v_mfma_f32_16x16x32_bf16 v[24:27], v[152:155], v[184:187], v[24:27]
	v_mfma_f32_16x16x32_bf16 v[32:35], v[160:163], v[184:187], v[32:35]
	v_mfma_f32_16x16x32_bf16 v[8:11], v[152:155], v[192:195], v[8:11]
	v_mfma_f32_16x16x32_bf16 v[12:15], v[160:163], v[192:195], v[12:15]
	s_barrier
	s_add_i32 s18, s88, 2
	s_cmp_lg_u32 s18, 8
	s_cbranch_scc1 .LBB0_397
	v_mov_b32_e32 v238, v1
	v_mov_b32_e32 v132, v235
	s_nop 0
	v_lshlrev_b32_e32 v133, 4, v238
	v_lshl_add_u32 v220, v132, 8, v133
	v_ashrrev_i32_e32 v221, 31, v220
	v_lshl_add_u64 v[132:133], s[44:45], 0, v[220:221]
	v_lshl_add_u64 v[134:135], v[132:133], 0, s[62:63]
	global_load_dwordx4 v[180:183], v[134:135], off
	global_load_dwordx4 v[188:191], v[134:135], off offset:2048
	global_load_dwordx4 v[168:171], v[134:135], off offset:1024
	global_load_dwordx4 v[176:179], v[134:135], off offset:3072
	v_lshl_add_u64 v[134:135], v[132:133], 0, s[60:61]
	global_load_dwordx4 v[184:187], v[134:135], off
	global_load_dwordx4 v[192:195], v[134:135], off offset:2048
	global_load_dwordx4 v[164:167], v[134:135], off offset:1024
	global_load_dwordx4 v[172:175], v[134:135], off offset:3072
	v_lshl_add_u64 v[134:135], v[132:133], 0, s[58:59]
	v_lshl_add_u64 v[136:137], v[132:133], 0, s[56:57]
	global_load_dwordx4 v[156:159], v[134:135], off
	global_load_dwordx4 v[160:163], v[134:135], off offset:2048
	global_load_dwordx4 v[148:151], v[134:135], off offset:1024
	global_load_dwordx4 v[152:155], v[134:135], off offset:3072
	global_load_dwordx4 v[140:143], v[136:137], off
	global_load_dwordx4 v[144:147], v[136:137], off offset:2048
	s_nop 0
	global_load_dwordx4 v[132:135], v[136:137], off offset:1024
	s_nop 0
	global_load_dwordx4 v[136:139], v[136:137], off offset:3072
	v_lshl_add_u32 v238, v238, 2, s77
	ds_read_b32 v239, v238
	s_waitcnt vmcnt(0)
	v_lshlrev_b32_e32 v242, 16, v189
	v_and_b32_e32 v243, 0xffff0000, v189
	v_lshlrev_b32_e32 v189, 16, v190
	s_waitcnt lgkmcnt(0)
	v_mul_f32_e32 v189, v239, v189
	v_lshlrev_b32_e32 v240, 16, v188
	v_and_b32_e32 v241, 0xffff0000, v188
	v_max_f32_e32 v189, 0xda24260, v189
	v_and_b32_e32 v244, 0xffff0000, v190
	v_mul_f32_e32 v188, v239, v240
	v_rcp_f32_e32 v190, v189
	v_mul_f32_e32 v189, v239, v241
	v_max_f32_e32 v188, 0xda24260, v188
	v_max_f32_e32 v189, 0xda24260, v189
	v_rcp_f32_e32 v188, v188
	v_rcp_f32_e32 v189, v189
	v_lshlrev_b32_e32 v240, 16, v180
	v_and_b32_e32 v241, 0xffff0000, v180
	v_mul_f32_e32 v180, v239, v244
	v_max_f32_e32 v180, 0xda24260, v180
	v_lshlrev_b32_e32 v245, 16, v191
	v_and_b32_e32 v246, 0xffff0000, v191
	v_rcp_f32_e32 v191, v180
	v_pk_mul_f32 v[188:189], v[188:189], v[240:241]
	v_mul_f32_e32 v180, v239, v242
	v_pk_mul_f32 v[128:129], v[128:129], v[188:189]
	v_lshlrev_b32_e32 v188, 16, v182
	v_and_b32_e32 v189, 0xffff0000, v182
	v_pk_mul_f32 v[188:189], v[190:191], v[188:189]
	v_max_f32_e32 v180, 0xda24260, v180
	v_pk_mul_f32 v[124:125], v[124:125], v[188:189]
	v_rcp_f32_e32 v188, v180
	v_mul_f32_e32 v180, v239, v245
	v_lshlrev_b32_e32 v190, 16, v181
	v_and_b32_e32 v191, 0xffff0000, v181
	v_mul_f32_e32 v181, v239, v246
	v_max_f32_e32 v180, 0xda24260, v180
	v_max_f32_e32 v181, 0xda24260, v181
	v_rcp_f32_e32 v180, v180
	v_mul_f32_e32 v182, v239, v243
	v_rcp_f32_e32 v181, v181
	v_max_f32_e32 v182, 0xda24260, v182
	v_rcp_f32_e32 v189, v182
	v_lshlrev_b32_e32 v182, 16, v183
	v_and_b32_e32 v183, 0xffff0000, v183
	v_pk_mul_f32 v[180:181], v[180:181], v[182:183]
	v_lshlrev_b32_e32 v182, 16, v177
	v_and_b32_e32 v183, 0xffff0000, v177
	v_lshlrev_b32_e32 v177, 16, v178
	v_mul_f32_e32 v177, v239, v177
	v_pk_mul_f32 v[188:189], v[188:189], v[190:191]
	v_pk_mul_f32 v[126:127], v[126:127], v[180:181]
	v_lshlrev_b32_e32 v180, 16, v176
	v_and_b32_e32 v181, 0xffff0000, v176
	v_max_f32_e32 v177, 0xda24260, v177
	v_pk_mul_f32 v[130:131], v[130:131], v[188:189]
	v_and_b32_e32 v188, 0xffff0000, v178
	v_mul_f32_e32 v176, v239, v180
	v_rcp_f32_e32 v178, v177
	v_mul_f32_e32 v177, v239, v181
	v_max_f32_e32 v176, 0xda24260, v176
	v_max_f32_e32 v177, 0xda24260, v177
	v_rcp_f32_e32 v176, v176
	v_rcp_f32_e32 v177, v177
	v_lshlrev_b32_e32 v180, 16, v168
	v_and_b32_e32 v181, 0xffff0000, v168
	v_mul_f32_e32 v168, v239, v188
	v_max_f32_e32 v168, 0xda24260, v168
	v_lshlrev_b32_e32 v189, 16, v179
	v_and_b32_e32 v190, 0xffff0000, v179
	v_rcp_f32_e32 v179, v168
	v_pk_mul_f32 v[176:177], v[176:177], v[180:181]
	v_mul_f32_e32 v168, v239, v182
	v_pk_mul_f32 v[120:121], v[120:121], v[176:177]
	v_lshlrev_b32_e32 v176, 16, v170
	v_and_b32_e32 v177, 0xffff0000, v170
	v_pk_mul_f32 v[176:177], v[178:179], v[176:177]
	v_max_f32_e32 v168, 0xda24260, v168
	v_mul_f32_e32 v170, v239, v183
	v_pk_mul_f32 v[116:117], v[116:117], v[176:177]
	v_rcp_f32_e32 v176, v168
	v_mul_f32_e32 v168, v239, v189
	v_max_f32_e32 v170, 0xda24260, v170
	v_lshlrev_b32_e32 v178, 16, v169
	v_and_b32_e32 v179, 0xffff0000, v169
	v_mul_f32_e32 v169, v239, v190
	v_max_f32_e32 v168, 0xda24260, v168
	v_rcp_f32_e32 v177, v170
	v_max_f32_e32 v169, 0xda24260, v169
	v_rcp_f32_e32 v168, v168
	v_rcp_f32_e32 v169, v169
	v_pk_mul_f32 v[176:177], v[176:177], v[178:179]
	v_lshlrev_b32_e32 v170, 16, v171
	v_and_b32_e32 v171, 0xffff0000, v171
	v_pk_mul_f32 v[122:123], v[122:123], v[176:177]
	v_pk_mul_f32 v[168:169], v[168:169], v[170:171]
	v_lshl_add_u64 v[176:177], s[64:65], 0, v[220:221]
	v_pk_mul_f32 v[118:119], v[118:119], v[168:169]
	global_load_dwordx4 v[180:183], v[176:177], off
	global_load_dwordx4 v[188:191], v[176:177], off offset:2048
	global_load_dwordx4 v[168:171], v[176:177], off offset:1024
	s_nop 0
	global_load_dwordx4 v[176:179], v[176:177], off offset:3072
	ds_read_b32 v239, v238 offset:64
	v_lshlrev_b32_e32 v242, 16, v193
	v_and_b32_e32 v243, 0xffff0000, v193
	v_lshlrev_b32_e32 v193, 16, v194
	v_lshlrev_b32_e32 v240, 16, v192
	s_waitcnt lgkmcnt(0)
	v_mul_f32_e32 v193, v239, v193
	v_and_b32_e32 v241, 0xffff0000, v192
	v_max_f32_e32 v193, 0xda24260, v193
	v_and_b32_e32 v244, 0xffff0000, v194
	v_mul_f32_e32 v192, v239, v240
	v_rcp_f32_e32 v194, v193
	v_mul_f32_e32 v193, v239, v241
	v_max_f32_e32 v192, 0xda24260, v192
	v_max_f32_e32 v193, 0xda24260, v193
	v_rcp_f32_e32 v192, v192
	v_rcp_f32_e32 v193, v193
	v_lshlrev_b32_e32 v240, 16, v184
	v_and_b32_e32 v241, 0xffff0000, v184
	v_mul_f32_e32 v184, v239, v244
	v_max_f32_e32 v184, 0xda24260, v184
	v_lshlrev_b32_e32 v245, 16, v195
	v_and_b32_e32 v246, 0xffff0000, v195
	v_rcp_f32_e32 v195, v184
	v_pk_mul_f32 v[192:193], v[192:193], v[240:241]
	v_mul_f32_e32 v184, v239, v242
	v_pk_mul_f32 v[112:113], v[112:113], v[192:193]
	v_lshlrev_b32_e32 v192, 16, v186
	v_and_b32_e32 v193, 0xffff0000, v186
	v_pk_mul_f32 v[192:193], v[194:195], v[192:193]
	v_max_f32_e32 v184, 0xda24260, v184
	v_pk_mul_f32 v[108:109], v[108:109], v[192:193]
	v_rcp_f32_e32 v192, v184
	v_mul_f32_e32 v184, v239, v245
	v_lshlrev_b32_e32 v194, 16, v185
	v_and_b32_e32 v195, 0xffff0000, v185
	v_mul_f32_e32 v185, v239, v246
	v_max_f32_e32 v184, 0xda24260, v184
	v_max_f32_e32 v185, 0xda24260, v185
	v_rcp_f32_e32 v184, v184
	v_mul_f32_e32 v186, v239, v243
	v_rcp_f32_e32 v185, v185
	v_max_f32_e32 v186, 0xda24260, v186
	v_rcp_f32_e32 v193, v186
	v_lshlrev_b32_e32 v186, 16, v187
	v_and_b32_e32 v187, 0xffff0000, v187
	v_pk_mul_f32 v[184:185], v[184:185], v[186:187]
	v_lshlrev_b32_e32 v186, 16, v173
	v_and_b32_e32 v187, 0xffff0000, v173
	v_lshlrev_b32_e32 v173, 16, v174
	v_mul_f32_e32 v173, v239, v173
	v_pk_mul_f32 v[192:193], v[192:193], v[194:195]
	v_pk_mul_f32 v[110:111], v[110:111], v[184:185]
	v_lshlrev_b32_e32 v184, 16, v172
	v_and_b32_e32 v185, 0xffff0000, v172
	v_max_f32_e32 v173, 0xda24260, v173
	v_pk_mul_f32 v[114:115], v[114:115], v[192:193]
	v_and_b32_e32 v192, 0xffff0000, v174
	v_mul_f32_e32 v172, v239, v184
	v_rcp_f32_e32 v174, v173
	v_mul_f32_e32 v173, v239, v185
	v_max_f32_e32 v172, 0xda24260, v172
	v_max_f32_e32 v173, 0xda24260, v173
	v_rcp_f32_e32 v172, v172
	v_rcp_f32_e32 v173, v173
	v_lshlrev_b32_e32 v184, 16, v164
	v_and_b32_e32 v185, 0xffff0000, v164
	v_mul_f32_e32 v164, v239, v192
	v_max_f32_e32 v164, 0xda24260, v164
	v_lshlrev_b32_e32 v193, 16, v175
	v_and_b32_e32 v194, 0xffff0000, v175
	v_rcp_f32_e32 v175, v164
	v_pk_mul_f32 v[172:173], v[172:173], v[184:185]
	v_mul_f32_e32 v164, v239, v186
	v_pk_mul_f32 v[104:105], v[104:105], v[172:173]
	v_lshlrev_b32_e32 v172, 16, v166
	v_and_b32_e32 v173, 0xffff0000, v166
	v_pk_mul_f32 v[172:173], v[174:175], v[172:173]
	v_max_f32_e32 v164, 0xda24260, v164
	v_mul_f32_e32 v166, v239, v187
	v_pk_mul_f32 v[100:101], v[100:101], v[172:173]
	v_rcp_f32_e32 v172, v164
	v_mul_f32_e32 v164, v239, v193
	v_max_f32_e32 v166, 0xda24260, v166
	v_lshlrev_b32_e32 v174, 16, v165
	v_and_b32_e32 v175, 0xffff0000, v165
	v_mul_f32_e32 v165, v239, v194
	v_max_f32_e32 v164, 0xda24260, v164
	v_rcp_f32_e32 v173, v166
	v_max_f32_e32 v165, 0xda24260, v165
	v_rcp_f32_e32 v164, v164
	v_rcp_f32_e32 v165, v165
	v_pk_mul_f32 v[172:173], v[172:173], v[174:175]
	v_lshlrev_b32_e32 v166, 16, v167
	v_and_b32_e32 v167, 0xffff0000, v167
	v_pk_mul_f32 v[106:107], v[106:107], v[172:173]
	v_pk_mul_f32 v[164:165], v[164:165], v[166:167]
	v_lshl_add_u64 v[172:173], s[66:67], 0, v[220:221]
	v_pk_mul_f32 v[102:103], v[102:103], v[164:165]
	global_load_dwordx4 v[184:187], v[172:173], off
	global_load_dwordx4 v[192:195], v[172:173], off offset:2048
	global_load_dwordx4 v[164:167], v[172:173], off offset:1024
	s_nop 0
	global_load_dwordx4 v[172:175], v[172:173], off offset:3072
	ds_read_b32 v239, v238 offset:128
	v_lshlrev_b32_e32 v242, 16, v161
	v_and_b32_e32 v243, 0xffff0000, v161
	v_lshlrev_b32_e32 v161, 16, v162
	v_lshlrev_b32_e32 v240, 16, v160
	s_waitcnt lgkmcnt(0)
	v_mul_f32_e32 v161, v239, v161
	v_and_b32_e32 v241, 0xffff0000, v160
	v_max_f32_e32 v161, 0xda24260, v161
	v_and_b32_e32 v244, 0xffff0000, v162
	v_mul_f32_e32 v160, v239, v240
	v_rcp_f32_e32 v162, v161
	v_mul_f32_e32 v161, v239, v241
	v_max_f32_e32 v160, 0xda24260, v160
	v_max_f32_e32 v161, 0xda24260, v161
	v_rcp_f32_e32 v160, v160
	v_rcp_f32_e32 v161, v161
	v_lshlrev_b32_e32 v240, 16, v156
	v_and_b32_e32 v241, 0xffff0000, v156
	v_mul_f32_e32 v156, v239, v244
	v_max_f32_e32 v156, 0xda24260, v156
	v_lshlrev_b32_e32 v245, 16, v163
	v_and_b32_e32 v246, 0xffff0000, v163
	v_rcp_f32_e32 v163, v156
	v_pk_mul_f32 v[160:161], v[160:161], v[240:241]
	v_mul_f32_e32 v156, v239, v242
	v_pk_mul_f32 v[96:97], v[96:97], v[160:161]
	v_lshlrev_b32_e32 v160, 16, v158
	v_and_b32_e32 v161, 0xffff0000, v158
	v_pk_mul_f32 v[160:161], v[162:163], v[160:161]
	v_max_f32_e32 v156, 0xda24260, v156
	v_pk_mul_f32 v[92:93], v[92:93], v[160:161]
	v_rcp_f32_e32 v160, v156
	v_mul_f32_e32 v156, v239, v245
	v_lshlrev_b32_e32 v162, 16, v157
	v_and_b32_e32 v163, 0xffff0000, v157
	v_mul_f32_e32 v157, v239, v246
	v_max_f32_e32 v156, 0xda24260, v156
	v_max_f32_e32 v157, 0xda24260, v157
	v_rcp_f32_e32 v156, v156
	v_mul_f32_e32 v158, v239, v243
	v_rcp_f32_e32 v157, v157
	v_max_f32_e32 v158, 0xda24260, v158
	v_rcp_f32_e32 v161, v158
	v_lshlrev_b32_e32 v158, 16, v159
	v_and_b32_e32 v159, 0xffff0000, v159
	v_pk_mul_f32 v[156:157], v[156:157], v[158:159]
	v_lshlrev_b32_e32 v158, 16, v153
	v_and_b32_e32 v159, 0xffff0000, v153
	v_lshlrev_b32_e32 v153, 16, v154
	v_mul_f32_e32 v153, v239, v153
	v_pk_mul_f32 v[160:161], v[160:161], v[162:163]
	v_pk_mul_f32 v[94:95], v[94:95], v[156:157]
	v_lshlrev_b32_e32 v156, 16, v152
	v_and_b32_e32 v157, 0xffff0000, v152
	v_max_f32_e32 v153, 0xda24260, v153
	v_pk_mul_f32 v[98:99], v[98:99], v[160:161]
	v_and_b32_e32 v160, 0xffff0000, v154
	v_mul_f32_e32 v152, v239, v156
	v_rcp_f32_e32 v154, v153
	v_mul_f32_e32 v153, v239, v157
	v_max_f32_e32 v152, 0xda24260, v152
	v_max_f32_e32 v153, 0xda24260, v153
	v_rcp_f32_e32 v152, v152
	v_rcp_f32_e32 v153, v153
	v_lshlrev_b32_e32 v156, 16, v148
	v_and_b32_e32 v157, 0xffff0000, v148
	v_mul_f32_e32 v148, v239, v160
	v_max_f32_e32 v148, 0xda24260, v148
	v_lshlrev_b32_e32 v161, 16, v155
	v_and_b32_e32 v162, 0xffff0000, v155
	v_rcp_f32_e32 v155, v148
	v_pk_mul_f32 v[152:153], v[152:153], v[156:157]
	v_mul_f32_e32 v148, v239, v158
	v_pk_mul_f32 v[88:89], v[88:89], v[152:153]
	v_lshlrev_b32_e32 v152, 16, v150
	v_and_b32_e32 v153, 0xffff0000, v150
	v_pk_mul_f32 v[152:153], v[154:155], v[152:153]
	v_max_f32_e32 v148, 0xda24260, v148
	v_mul_f32_e32 v150, v239, v159
	v_pk_mul_f32 v[84:85], v[84:85], v[152:153]
	v_rcp_f32_e32 v152, v148
	v_mul_f32_e32 v148, v239, v161
	v_max_f32_e32 v150, 0xda24260, v150
	v_lshlrev_b32_e32 v154, 16, v149
	v_and_b32_e32 v155, 0xffff0000, v149
	v_mul_f32_e32 v149, v239, v162
	v_max_f32_e32 v148, 0xda24260, v148
	v_rcp_f32_e32 v153, v150
	v_max_f32_e32 v149, 0xda24260, v149
	v_rcp_f32_e32 v148, v148
	v_rcp_f32_e32 v149, v149
	v_pk_mul_f32 v[152:153], v[152:153], v[154:155]
	v_lshlrev_b32_e32 v150, 16, v151
	v_and_b32_e32 v151, 0xffff0000, v151
	v_pk_mul_f32 v[90:91], v[90:91], v[152:153]
	v_pk_mul_f32 v[148:149], v[148:149], v[150:151]
	v_lshl_add_u64 v[152:153], s[68:69], 0, v[220:221]
	v_pk_mul_f32 v[86:87], v[86:87], v[148:149]
	global_load_dwordx4 v[156:159], v[152:153], off
	global_load_dwordx4 v[160:163], v[152:153], off offset:2048
	global_load_dwordx4 v[148:151], v[152:153], off offset:1024
	s_nop 0
	global_load_dwordx4 v[152:155], v[152:153], off offset:3072
	ds_read_b32 v239, v238 offset:192
	v_lshlrev_b32_e32 v242, 16, v145
	v_and_b32_e32 v243, 0xffff0000, v145
	v_lshlrev_b32_e32 v145, 16, v146
	v_lshlrev_b32_e32 v240, 16, v144
	s_waitcnt lgkmcnt(0)
	v_mul_f32_e32 v145, v239, v145
	v_and_b32_e32 v241, 0xffff0000, v144
	v_max_f32_e32 v145, 0xda24260, v145
	v_and_b32_e32 v244, 0xffff0000, v146
	v_mul_f32_e32 v144, v239, v240
	v_rcp_f32_e32 v146, v145
	v_mul_f32_e32 v145, v239, v241
	v_max_f32_e32 v144, 0xda24260, v144
	v_max_f32_e32 v145, 0xda24260, v145
	v_rcp_f32_e32 v144, v144
	v_rcp_f32_e32 v145, v145
	v_lshlrev_b32_e32 v240, 16, v140
	v_and_b32_e32 v241, 0xffff0000, v140
	v_mul_f32_e32 v140, v239, v244
	v_max_f32_e32 v140, 0xda24260, v140
	v_lshlrev_b32_e32 v245, 16, v147
	v_and_b32_e32 v246, 0xffff0000, v147
	v_rcp_f32_e32 v147, v140
	v_pk_mul_f32 v[144:145], v[144:145], v[240:241]
	v_mul_f32_e32 v140, v239, v242
	v_pk_mul_f32 v[80:81], v[80:81], v[144:145]
	v_lshlrev_b32_e32 v144, 16, v142
	v_and_b32_e32 v145, 0xffff0000, v142
	v_pk_mul_f32 v[144:145], v[146:147], v[144:145]
	v_max_f32_e32 v140, 0xda24260, v140
	v_pk_mul_f32 v[76:77], v[76:77], v[144:145]
	v_rcp_f32_e32 v144, v140
	v_mul_f32_e32 v140, v239, v245
	v_lshlrev_b32_e32 v146, 16, v141
	v_and_b32_e32 v147, 0xffff0000, v141
	v_mul_f32_e32 v141, v239, v246
	v_max_f32_e32 v140, 0xda24260, v140
	v_max_f32_e32 v141, 0xda24260, v141
	v_rcp_f32_e32 v140, v140
	v_mul_f32_e32 v142, v239, v243
	v_rcp_f32_e32 v141, v141
	v_max_f32_e32 v142, 0xda24260, v142
	v_rcp_f32_e32 v145, v142
	v_lshlrev_b32_e32 v142, 16, v143
	v_and_b32_e32 v143, 0xffff0000, v143
	v_pk_mul_f32 v[140:141], v[140:141], v[142:143]
	v_lshlrev_b32_e32 v142, 16, v137
	v_and_b32_e32 v143, 0xffff0000, v137
	v_lshlrev_b32_e32 v137, 16, v138
	v_mul_f32_e32 v137, v239, v137
	v_pk_mul_f32 v[144:145], v[144:145], v[146:147]
	v_pk_mul_f32 v[78:79], v[78:79], v[140:141]
	v_lshlrev_b32_e32 v140, 16, v136
	v_and_b32_e32 v141, 0xffff0000, v136
	v_max_f32_e32 v137, 0xda24260, v137
	v_pk_mul_f32 v[82:83], v[82:83], v[144:145]
	v_and_b32_e32 v144, 0xffff0000, v138
	v_mul_f32_e32 v136, v239, v140
	v_rcp_f32_e32 v138, v137
	v_mul_f32_e32 v137, v239, v141
	v_max_f32_e32 v136, 0xda24260, v136
	v_max_f32_e32 v137, 0xda24260, v137
	v_rcp_f32_e32 v136, v136
	v_rcp_f32_e32 v137, v137
	v_lshlrev_b32_e32 v140, 16, v132
	v_and_b32_e32 v141, 0xffff0000, v132
	v_mul_f32_e32 v132, v239, v144
	v_max_f32_e32 v132, 0xda24260, v132
	v_lshlrev_b32_e32 v145, 16, v139
	v_and_b32_e32 v146, 0xffff0000, v139
	v_rcp_f32_e32 v139, v132
	v_pk_mul_f32 v[136:137], v[136:137], v[140:141]
	v_mul_f32_e32 v132, v239, v142
	v_pk_mul_f32 v[72:73], v[72:73], v[136:137]
	v_lshlrev_b32_e32 v136, 16, v134
	v_and_b32_e32 v137, 0xffff0000, v134
	v_pk_mul_f32 v[136:137], v[138:139], v[136:137]
	v_max_f32_e32 v132, 0xda24260, v132
	v_mul_f32_e32 v134, v239, v143
	v_pk_mul_f32 v[68:69], v[68:69], v[136:137]
	v_rcp_f32_e32 v136, v132
	v_mul_f32_e32 v132, v239, v145
	v_max_f32_e32 v134, 0xda24260, v134
	v_lshlrev_b32_e32 v138, 16, v133
	v_and_b32_e32 v139, 0xffff0000, v133
	v_mul_f32_e32 v133, v239, v146
	v_max_f32_e32 v132, 0xda24260, v132
	v_rcp_f32_e32 v137, v134
	v_max_f32_e32 v133, 0xda24260, v133
	v_rcp_f32_e32 v132, v132
	v_rcp_f32_e32 v133, v133
	v_pk_mul_f32 v[136:137], v[136:137], v[138:139]
	v_lshlrev_b32_e32 v134, 16, v135
	v_and_b32_e32 v135, 0xffff0000, v135
	v_pk_mul_f32 v[74:75], v[74:75], v[136:137]
	v_pk_mul_f32 v[132:133], v[132:133], v[134:135]
	v_lshl_add_u64 v[136:137], s[70:71], 0, v[220:221]
	v_pk_mul_f32 v[70:71], v[70:71], v[132:133]
	global_load_dwordx4 v[140:143], v[136:137], off
	global_load_dwordx4 v[144:147], v[136:137], off offset:2048
	global_load_dwordx4 v[132:135], v[136:137], off offset:1024
	s_nop 0
	global_load_dwordx4 v[136:139], v[136:137], off offset:3072
	ds_read_b32 v239, v238 offset:512
	s_waitcnt vmcnt(14)
	v_lshlrev_b32_e32 v240, 16, v189
	v_and_b32_e32 v241, 0xffff0000, v189
	v_lshlrev_b32_e32 v189, 16, v190
	v_lshlrev_b32_e32 v220, 16, v188
	s_waitcnt lgkmcnt(0)
	v_mul_f32_e32 v189, v239, v189
	v_and_b32_e32 v221, 0xffff0000, v188
	v_max_f32_e32 v189, 0xda24260, v189
	v_and_b32_e32 v242, 0xffff0000, v190
	v_mul_f32_e32 v188, v239, v220
	v_rcp_f32_e32 v190, v189
	v_mul_f32_e32 v189, v239, v221
	v_max_f32_e32 v188, 0xda24260, v188
	v_max_f32_e32 v189, 0xda24260, v189
	v_rcp_f32_e32 v188, v188
	v_rcp_f32_e32 v189, v189
	v_lshlrev_b32_e32 v220, 16, v180
	v_and_b32_e32 v221, 0xffff0000, v180
	v_mul_f32_e32 v180, v239, v242
	v_max_f32_e32 v180, 0xda24260, v180
	v_lshlrev_b32_e32 v243, 16, v191
	v_and_b32_e32 v244, 0xffff0000, v191
	v_rcp_f32_e32 v191, v180
	v_pk_mul_f32 v[188:189], v[188:189], v[220:221]
	v_mul_f32_e32 v180, v239, v240
	v_pk_mul_f32 v[52:53], v[52:53], v[188:189]
	v_lshlrev_b32_e32 v188, 16, v182
	v_and_b32_e32 v189, 0xffff0000, v182
	v_pk_mul_f32 v[188:189], v[190:191], v[188:189]
	v_max_f32_e32 v180, 0xda24260, v180
	v_pk_mul_f32 v[60:61], v[60:61], v[188:189]
	v_rcp_f32_e32 v188, v180
	v_mul_f32_e32 v180, v239, v243
	v_lshlrev_b32_e32 v190, 16, v181
	v_and_b32_e32 v191, 0xffff0000, v181
	v_mul_f32_e32 v181, v239, v244
	v_max_f32_e32 v180, 0xda24260, v180
	v_max_f32_e32 v181, 0xda24260, v181
	v_rcp_f32_e32 v180, v180
	v_mul_f32_e32 v182, v239, v241
	v_rcp_f32_e32 v181, v181
	v_max_f32_e32 v182, 0xda24260, v182
	v_rcp_f32_e32 v189, v182
	v_lshlrev_b32_e32 v182, 16, v183
	v_and_b32_e32 v183, 0xffff0000, v183
	v_pk_mul_f32 v[180:181], v[180:181], v[182:183]
	s_waitcnt vmcnt(12)
	v_lshlrev_b32_e32 v182, 16, v177
	v_and_b32_e32 v183, 0xffff0000, v177
	v_lshlrev_b32_e32 v177, 16, v178
	v_mul_f32_e32 v177, v239, v177
	v_pk_mul_f32 v[188:189], v[188:189], v[190:191]
	v_pk_mul_f32 v[62:63], v[62:63], v[180:181]
	v_lshlrev_b32_e32 v180, 16, v176
	v_and_b32_e32 v181, 0xffff0000, v176
	v_max_f32_e32 v177, 0xda24260, v177
	v_pk_mul_f32 v[54:55], v[54:55], v[188:189]
	v_and_b32_e32 v188, 0xffff0000, v178
	v_mul_f32_e32 v176, v239, v180
	v_rcp_f32_e32 v178, v177
	v_mul_f32_e32 v177, v239, v181
	v_max_f32_e32 v176, 0xda24260, v176
	v_max_f32_e32 v177, 0xda24260, v177
	v_rcp_f32_e32 v176, v176
	v_rcp_f32_e32 v177, v177
	v_lshlrev_b32_e32 v180, 16, v168
	v_and_b32_e32 v181, 0xffff0000, v168
	v_mul_f32_e32 v168, v239, v188
	v_max_f32_e32 v168, 0xda24260, v168
	v_lshlrev_b32_e32 v189, 16, v179
	v_and_b32_e32 v190, 0xffff0000, v179
	v_rcp_f32_e32 v179, v168
	v_pk_mul_f32 v[176:177], v[176:177], v[180:181]
	v_mul_f32_e32 v168, v239, v182
	v_pk_mul_f32 v[56:57], v[56:57], v[176:177]
	v_lshlrev_b32_e32 v176, 16, v170
	v_and_b32_e32 v177, 0xffff0000, v170
	v_mul_f32_e32 v170, v239, v183
	v_pk_mul_f32 v[176:177], v[178:179], v[176:177]
	v_max_f32_e32 v168, 0xda24260, v168
	v_max_f32_e32 v170, 0xda24260, v170
	v_pk_mul_f32 v[64:65], v[64:65], v[176:177]
	v_rcp_f32_e32 v176, v168
	v_rcp_f32_e32 v177, v170
	v_mul_f32_e32 v168, v239, v189
	v_lshlrev_b32_e32 v178, 16, v169
	v_and_b32_e32 v179, 0xffff0000, v169
	v_mul_f32_e32 v169, v239, v190
	v_max_f32_e32 v168, 0xda24260, v168
	v_max_f32_e32 v169, 0xda24260, v169
	v_rcp_f32_e32 v168, v168
	v_rcp_f32_e32 v169, v169
	v_pk_mul_f32 v[176:177], v[176:177], v[178:179]
	ds_read_b32 v178, v238 offset:576
	v_lshlrev_b32_e32 v170, 16, v171
	v_and_b32_e32 v171, 0xffff0000, v171
	v_pk_mul_f32 v[168:169], v[168:169], v[170:171]
	v_pk_mul_f32 v[58:59], v[58:59], v[176:177]
	v_pk_mul_f32 v[66:67], v[66:67], v[168:169]
	s_waitcnt vmcnt(10)
	v_lshlrev_b32_e32 v168, 16, v192
	v_and_b32_e32 v169, 0xffff0000, v192
	s_waitcnt lgkmcnt(0)
	v_mul_f32_e32 v168, v178, v168
	v_mul_f32_e32 v169, v178, v169
	v_max_f32_e32 v168, 0xda24260, v168
	v_max_f32_e32 v169, 0xda24260, v169
	v_rcp_f32_e32 v168, v168
	v_rcp_f32_e32 v169, v169
	v_lshlrev_b32_e32 v176, 16, v184
	v_and_b32_e32 v177, 0xffff0000, v184
	v_lshlrev_b32_e32 v170, 16, v194
	v_and_b32_e32 v171, 0xffff0000, v194
	v_pk_mul_f32 v[168:169], v[168:169], v[176:177]
	v_mul_f32_e32 v170, v178, v170
	v_pk_mul_f32 v[36:37], v[36:37], v[168:169]
	v_mul_f32_e32 v168, v178, v171
	v_max_f32_e32 v170, 0xda24260, v170
	v_max_f32_e32 v168, 0xda24260, v168
	v_rcp_f32_e32 v170, v170
	v_rcp_f32_e32 v171, v168
	v_lshlrev_b32_e32 v168, 16, v186
	v_and_b32_e32 v169, 0xffff0000, v186
	v_lshlrev_b32_e32 v181, 16, v195
	v_pk_mul_f32 v[168:169], v[170:171], v[168:169]
	v_lshlrev_b32_e32 v179, 16, v193
	v_pk_mul_f32 v[44:45], v[44:45], v[168:169]
	v_mul_f32_e32 v169, v178, v181
	v_and_b32_e32 v180, 0xffff0000, v193
	v_max_f32_e32 v169, 0xda24260, v169
	v_mul_f32_e32 v168, v178, v179
	v_rcp_f32_e32 v170, v169
	v_mul_f32_e32 v169, v178, v180
	v_max_f32_e32 v168, 0xda24260, v168
	v_max_f32_e32 v169, 0xda24260, v169
	v_rcp_f32_e32 v168, v168
	v_rcp_f32_e32 v169, v169
	v_lshlrev_b32_e32 v176, 16, v185
	v_and_b32_e32 v177, 0xffff0000, v185
	v_and_b32_e32 v182, 0xffff0000, v195
	v_pk_mul_f32 v[168:169], v[168:169], v[176:177]
	s_waitcnt vmcnt(8)
	v_lshlrev_b32_e32 v176, 16, v173
	v_pk_mul_f32 v[38:39], v[38:39], v[168:169]
	v_mul_f32_e32 v168, v178, v182
	v_max_f32_e32 v168, 0xda24260, v168
	v_rcp_f32_e32 v171, v168
	v_lshlrev_b32_e32 v168, 16, v187
	v_and_b32_e32 v169, 0xffff0000, v187
	v_and_b32_e32 v177, 0xffff0000, v173
	v_pk_mul_f32 v[168:169], v[170:171], v[168:169]
	v_lshlrev_b32_e32 v170, 16, v174
	v_pk_mul_f32 v[46:47], v[46:47], v[168:169]
	v_lshlrev_b32_e32 v168, 16, v172
	v_and_b32_e32 v169, 0xffff0000, v172
	v_mul_f32_e32 v168, v178, v168
	v_mul_f32_e32 v169, v178, v169
	v_and_b32_e32 v171, 0xffff0000, v174
	v_max_f32_e32 v168, 0xda24260, v168
	v_max_f32_e32 v169, 0xda24260, v169
	v_rcp_f32_e32 v168, v168
	v_mul_f32_e32 v170, v178, v170
	v_rcp_f32_e32 v169, v169
	v_lshlrev_b32_e32 v172, 16, v164
	v_and_b32_e32 v173, 0xffff0000, v164
	v_mul_f32_e32 v164, v178, v171
	v_max_f32_e32 v170, 0xda24260, v170
	v_max_f32_e32 v164, 0xda24260, v164
	v_rcp_f32_e32 v170, v170
	v_rcp_f32_e32 v171, v164
	v_pk_mul_f32 v[168:169], v[168:169], v[172:173]
	v_mul_f32_e32 v164, v178, v176
	v_pk_mul_f32 v[40:41], v[40:41], v[168:169]
	v_lshlrev_b32_e32 v168, 16, v166
	v_and_b32_e32 v169, 0xffff0000, v166
	v_lshlrev_b32_e32 v174, 16, v175
	v_and_b32_e32 v175, 0xffff0000, v175
	v_pk_mul_f32 v[168:169], v[170:171], v[168:169]
	v_max_f32_e32 v164, 0xda24260, v164
	v_pk_mul_f32 v[48:49], v[48:49], v[168:169]
	v_rcp_f32_e32 v168, v164
	v_mul_f32_e32 v164, v178, v174
	v_lshlrev_b32_e32 v170, 16, v165
	v_and_b32_e32 v171, 0xffff0000, v165
	v_mul_f32_e32 v165, v178, v175
	v_max_f32_e32 v164, 0xda24260, v164
	v_max_f32_e32 v165, 0xda24260, v165
	v_rcp_f32_e32 v164, v164
	v_rcp_f32_e32 v165, v165
	v_mul_f32_e32 v166, v178, v177
	v_max_f32_e32 v166, 0xda24260, v166
	v_rcp_f32_e32 v169, v166
	v_lshlrev_b32_e32 v166, 16, v167
	v_and_b32_e32 v167, 0xffff0000, v167
	v_pk_mul_f32 v[164:165], v[164:165], v[166:167]
	ds_read_b32 v166, v238 offset:640
	v_pk_mul_f32 v[168:169], v[168:169], v[170:171]
	s_waitcnt vmcnt(6)
	v_lshlrev_b32_e32 v167, 16, v161
	v_pk_mul_f32 v[42:43], v[42:43], v[168:169]
	v_and_b32_e32 v168, 0xffff0000, v161
	v_lshlrev_b32_e32 v161, 16, v162
	s_waitcnt lgkmcnt(0)
	v_mul_f32_e32 v161, v166, v161
	v_pk_mul_f32 v[50:51], v[50:51], v[164:165]
	v_lshlrev_b32_e32 v164, 16, v160
	v_and_b32_e32 v165, 0xffff0000, v160
	v_max_f32_e32 v161, 0xda24260, v161
	v_and_b32_e32 v169, 0xffff0000, v162
	v_mul_f32_e32 v160, v166, v164
	v_rcp_f32_e32 v162, v161
	v_mul_f32_e32 v161, v166, v165
	v_max_f32_e32 v160, 0xda24260, v160
	v_max_f32_e32 v161, 0xda24260, v161
	v_rcp_f32_e32 v160, v160
	v_rcp_f32_e32 v161, v161
	v_lshlrev_b32_e32 v164, 16, v156
	v_and_b32_e32 v165, 0xffff0000, v156
	v_mul_f32_e32 v156, v166, v169
	v_max_f32_e32 v156, 0xda24260, v156
	v_lshlrev_b32_e32 v170, 16, v163
	v_and_b32_e32 v171, 0xffff0000, v163
	v_rcp_f32_e32 v163, v156
	v_pk_mul_f32 v[160:161], v[160:161], v[164:165]
	v_mul_f32_e32 v156, v166, v167
	v_pk_mul_f32 v[20:21], v[20:21], v[160:161]
	v_lshlrev_b32_e32 v160, 16, v158
	v_and_b32_e32 v161, 0xffff0000, v158
	v_pk_mul_f32 v[160:161], v[162:163], v[160:161]
	v_max_f32_e32 v156, 0xda24260, v156
	v_pk_mul_f32 v[28:29], v[28:29], v[160:161]
	v_rcp_f32_e32 v160, v156
	v_mul_f32_e32 v156, v166, v170
	v_lshlrev_b32_e32 v162, 16, v157
	v_and_b32_e32 v163, 0xffff0000, v157
	v_mul_f32_e32 v157, v166, v171
	v_max_f32_e32 v156, 0xda24260, v156
	v_max_f32_e32 v157, 0xda24260, v157
	v_rcp_f32_e32 v156, v156
	v_mul_f32_e32 v158, v166, v168
	v_rcp_f32_e32 v157, v157
	v_max_f32_e32 v158, 0xda24260, v158
	v_rcp_f32_e32 v161, v158
	v_lshlrev_b32_e32 v158, 16, v159
	v_and_b32_e32 v159, 0xffff0000, v159
	v_pk_mul_f32 v[156:157], v[156:157], v[158:159]
	s_waitcnt vmcnt(4)
	v_lshlrev_b32_e32 v158, 16, v153
	v_and_b32_e32 v159, 0xffff0000, v153
	v_lshlrev_b32_e32 v153, 16, v154
	v_mul_f32_e32 v153, v166, v153
	v_pk_mul_f32 v[160:161], v[160:161], v[162:163]
	v_pk_mul_f32 v[30:31], v[30:31], v[156:157]
	v_lshlrev_b32_e32 v156, 16, v152
	v_and_b32_e32 v157, 0xffff0000, v152
	v_max_f32_e32 v153, 0xda24260, v153
	v_pk_mul_f32 v[22:23], v[22:23], v[160:161]
	v_and_b32_e32 v160, 0xffff0000, v154
	v_mul_f32_e32 v152, v166, v156
	v_rcp_f32_e32 v154, v153
	v_mul_f32_e32 v153, v166, v157
	v_max_f32_e32 v152, 0xda24260, v152
	v_max_f32_e32 v153, 0xda24260, v153
	v_rcp_f32_e32 v152, v152
	v_rcp_f32_e32 v153, v153
	v_lshlrev_b32_e32 v156, 16, v148
	v_and_b32_e32 v157, 0xffff0000, v148
	v_mul_f32_e32 v148, v166, v160
	v_max_f32_e32 v148, 0xda24260, v148
	v_lshlrev_b32_e32 v161, 16, v155
	v_and_b32_e32 v162, 0xffff0000, v155
	v_rcp_f32_e32 v155, v148
	v_pk_mul_f32 v[152:153], v[152:153], v[156:157]
	v_mul_f32_e32 v148, v166, v158
	v_pk_mul_f32 v[24:25], v[24:25], v[152:153]
	v_lshlrev_b32_e32 v152, 16, v150
	v_and_b32_e32 v153, 0xffff0000, v150
	v_pk_mul_f32 v[152:153], v[154:155], v[152:153]
	v_max_f32_e32 v148, 0xda24260, v148
	v_pk_mul_f32 v[32:33], v[32:33], v[152:153]
	v_rcp_f32_e32 v152, v148
	v_mul_f32_e32 v148, v166, v161
	v_lshlrev_b32_e32 v154, 16, v149
	v_and_b32_e32 v155, 0xffff0000, v149
	v_mul_f32_e32 v149, v166, v162
	v_max_f32_e32 v148, 0xda24260, v148
	v_max_f32_e32 v149, 0xda24260, v149
	v_rcp_f32_e32 v148, v148
	v_rcp_f32_e32 v149, v149
	v_mul_f32_e32 v150, v166, v159
	v_max_f32_e32 v150, 0xda24260, v150
	v_rcp_f32_e32 v153, v150
	v_lshlrev_b32_e32 v150, 16, v151
	v_and_b32_e32 v151, 0xffff0000, v151
	v_pk_mul_f32 v[148:149], v[148:149], v[150:151]
	ds_read_b32 v150, v238 offset:704
	v_pk_mul_f32 v[152:153], v[152:153], v[154:155]
	s_waitcnt vmcnt(2)
	v_lshlrev_b32_e32 v151, 16, v145
	v_pk_mul_f32 v[26:27], v[26:27], v[152:153]
	v_and_b32_e32 v152, 0xffff0000, v145
	v_lshlrev_b32_e32 v145, 16, v146
	s_waitcnt lgkmcnt(0)
	v_mul_f32_e32 v145, v150, v145
	v_pk_mul_f32 v[34:35], v[34:35], v[148:149]
	v_lshlrev_b32_e32 v148, 16, v144
	v_and_b32_e32 v149, 0xffff0000, v144
	v_max_f32_e32 v145, 0xda24260, v145
	v_and_b32_e32 v153, 0xffff0000, v146
	v_mul_f32_e32 v144, v150, v148
	v_rcp_f32_e32 v146, v145
	v_mul_f32_e32 v145, v150, v149
	v_max_f32_e32 v144, 0xda24260, v144
	v_max_f32_e32 v145, 0xda24260, v145
	v_rcp_f32_e32 v144, v144
	v_rcp_f32_e32 v145, v145
	v_lshlrev_b32_e32 v148, 16, v140
	v_and_b32_e32 v149, 0xffff0000, v140
	v_mul_f32_e32 v140, v150, v153
	v_max_f32_e32 v140, 0xda24260, v140
	v_lshlrev_b32_e32 v154, 16, v147
	v_and_b32_e32 v155, 0xffff0000, v147
	v_rcp_f32_e32 v147, v140
	v_pk_mul_f32 v[144:145], v[144:145], v[148:149]
	v_mul_f32_e32 v140, v150, v151
	v_pk_mul_f32 v[4:5], v[4:5], v[144:145]
	v_lshlrev_b32_e32 v144, 16, v142
	v_and_b32_e32 v145, 0xffff0000, v142
	v_pk_mul_f32 v[144:145], v[146:147], v[144:145]
	v_max_f32_e32 v140, 0xda24260, v140
	v_pk_mul_f32 v[16:17], v[16:17], v[144:145]
	v_rcp_f32_e32 v144, v140
	v_mul_f32_e32 v140, v150, v154
	v_lshlrev_b32_e32 v146, 16, v141
	v_and_b32_e32 v147, 0xffff0000, v141
	v_mul_f32_e32 v141, v150, v155
	v_max_f32_e32 v140, 0xda24260, v140
	v_max_f32_e32 v141, 0xda24260, v141
	v_rcp_f32_e32 v140, v140
	v_mul_f32_e32 v142, v150, v152
	v_rcp_f32_e32 v141, v141
	v_max_f32_e32 v142, 0xda24260, v142
	v_rcp_f32_e32 v145, v142
	v_lshlrev_b32_e32 v142, 16, v143
	v_and_b32_e32 v143, 0xffff0000, v143
	v_pk_mul_f32 v[140:141], v[140:141], v[142:143]
	s_waitcnt vmcnt(0)
	v_lshlrev_b32_e32 v142, 16, v137
	v_and_b32_e32 v143, 0xffff0000, v137
	v_lshlrev_b32_e32 v137, 16, v138
	v_mul_f32_e32 v137, v150, v137
	v_pk_mul_f32 v[144:145], v[144:145], v[146:147]
	v_pk_mul_f32 v[18:19], v[18:19], v[140:141]
	v_lshlrev_b32_e32 v140, 16, v136
	v_and_b32_e32 v141, 0xffff0000, v136
	v_max_f32_e32 v137, 0xda24260, v137
	v_pk_mul_f32 v[6:7], v[6:7], v[144:145]
	v_and_b32_e32 v144, 0xffff0000, v138
	v_mul_f32_e32 v136, v150, v140
	v_rcp_f32_e32 v138, v137
	v_mul_f32_e32 v137, v150, v141
	v_max_f32_e32 v136, 0xda24260, v136
	v_max_f32_e32 v137, 0xda24260, v137
	v_rcp_f32_e32 v136, v136
	v_rcp_f32_e32 v137, v137
	v_lshlrev_b32_e32 v140, 16, v132
	v_and_b32_e32 v141, 0xffff0000, v132
	v_mul_f32_e32 v132, v150, v144
	v_max_f32_e32 v132, 0xda24260, v132
	v_lshlrev_b32_e32 v145, 16, v139
	v_and_b32_e32 v146, 0xffff0000, v139
	v_rcp_f32_e32 v139, v132
	v_pk_mul_f32 v[136:137], v[136:137], v[140:141]
	v_mul_f32_e32 v132, v150, v142
	v_pk_mul_f32 v[8:9], v[8:9], v[136:137]
	v_lshlrev_b32_e32 v136, 16, v134
	v_and_b32_e32 v137, 0xffff0000, v134
	v_pk_mul_f32 v[136:137], v[138:139], v[136:137]
	v_max_f32_e32 v132, 0xda24260, v132
	v_pk_mul_f32 v[12:13], v[12:13], v[136:137]
	v_rcp_f32_e32 v136, v132
	v_mul_f32_e32 v132, v150, v145
	v_mul_f32_e32 v134, v150, v143
	v_lshlrev_b32_e32 v138, 16, v133
	v_and_b32_e32 v139, 0xffff0000, v133
	v_mul_f32_e32 v133, v150, v146
	v_max_f32_e32 v132, 0xda24260, v132
	v_max_f32_e32 v134, 0xda24260, v134
	v_max_f32_e32 v133, 0xda24260, v133
	v_rcp_f32_e32 v132, v132
	v_rcp_f32_e32 v137, v134
	v_rcp_f32_e32 v133, v133
	v_lshlrev_b32_e32 v134, 16, v135
	v_and_b32_e32 v135, 0xffff0000, v135
	v_pk_mul_f32 v[136:137], v[136:137], v[138:139]
	v_pk_mul_f32 v[132:133], v[132:133], v[134:135]
	v_pk_mul_f32 v[10:11], v[10:11], v[136:137]
	v_pk_mul_f32 v[14:15], v[14:15], v[132:133]

.LBB0_752:
	s_add_u32 s20, s18, 0xfffc0080
	s_addc_u32 s21, s19, -1
	s_add_i32 s41, 0, 0x10000
	s_cmp_eq_u32 s40, 12
	s_cselect_b32 s23, s15, s21
	s_cselect_b32 s22, s17, s20
	v_add_u32_e32 v2, s41, v157
	s_cselect_b32 s21, s24, s27
	s_cselect_b32 s20, s25, s26
	s_add_i32 s55, 0, 0x14000
	ds_read_b128 v[144:147], v2
	ds_read_b128 v[148:151], v2 offset:1024
	ds_read_b128 v[152:155], v2 offset:2048
	ds_read_b128 v[160:163], v2 offset:3072
	v_add_u32_e32 v2, s55, v157
	ds_read_b128 v[164:167], v2
	ds_read_b128 v[168:171], v2 offset:1024
	ds_read_b128 v[172:175], v2 offset:2048
	ds_read_b128 v[176:179], v2 offset:3072
	v_lshl_add_u64 v[234:235], s[18:19], 0, v[140:141]
	s_add_i32 m0, s36, 0xc000
	ds_read_b128 v[180:183], v158
	ds_read_b128 v[184:187], v158 offset:1024
	ds_read_b128 v[188:191], v158 offset:2048
	ds_read_b128 v[192:195], v158 offset:3072
	ds_read_b128 v[206:209], v158 offset:4096
	ds_read_b128 v[210:213], v158 offset:5120
	ds_read_b128 v[214:217], v158 offset:6144
	ds_read_b128 v[218:221], v158 offset:7168
	global_load_lds_dwordx4 v[234:235], off
	v_lshl_add_u64 v[234:235], s[18:19], 0, v[142:143]
	s_add_i32 m0, s36, 0xe000
	s_nop 0
	global_load_lds_dwordx4 v[234:235], off
	s_waitcnt vmcnt(8)
	s_waitcnt lgkmcnt(0)
	s_barrier
	s_waitcnt lgkmcnt(0)
	v_mfma_f32_16x16x32_bf16 v[120:123], v[144:147], v[180:183], v[120:123]
	v_mfma_f32_16x16x32_bf16 v[116:119], v[152:155], v[180:183], v[116:119]
	v_mfma_f32_16x16x32_bf16 v[104:107], v[144:147], v[188:191], v[104:107]
	v_mfma_f32_16x16x32_bf16 v[100:103], v[152:155], v[188:191], v[100:103]
	v_mfma_f32_16x16x32_bf16 v[88:91], v[144:147], v[206:209], v[88:91]
	v_mfma_f32_16x16x32_bf16 v[84:87], v[152:155], v[206:209], v[84:87]
	v_mfma_f32_16x16x32_bf16 v[72:75], v[144:147], v[214:217], v[72:75]
	v_mfma_f32_16x16x32_bf16 v[68:71], v[152:155], v[214:217], v[68:71]
	v_mfma_f32_16x16x32_bf16 v[120:123], v[148:151], v[184:187], v[120:123]
	v_mfma_f32_16x16x32_bf16 v[116:119], v[160:163], v[184:187], v[116:119]
	v_mfma_f32_16x16x32_bf16 v[104:107], v[148:151], v[192:195], v[104:107]
	v_mfma_f32_16x16x32_bf16 v[100:103], v[160:163], v[192:195], v[100:103]
	v_mfma_f32_16x16x32_bf16 v[88:91], v[148:151], v[210:213], v[88:91]
	v_mfma_f32_16x16x32_bf16 v[84:87], v[160:163], v[210:213], v[84:87]
	v_mfma_f32_16x16x32_bf16 v[72:75], v[148:151], v[218:221], v[72:75]
	v_mfma_f32_16x16x32_bf16 v[68:71], v[160:163], v[218:221], v[68:71]
	v_mfma_f32_16x16x32_bf16 v[128:131], v[164:167], v[180:183], v[128:131]
	v_mfma_f32_16x16x32_bf16 v[124:127], v[172:175], v[180:183], v[124:127]
	v_mfma_f32_16x16x32_bf16 v[112:115], v[164:167], v[188:191], v[112:115]
	v_mfma_f32_16x16x32_bf16 v[108:111], v[172:175], v[188:191], v[108:111]
	v_mfma_f32_16x16x32_bf16 v[96:99], v[164:167], v[206:209], v[96:99]
	v_mfma_f32_16x16x32_bf16 v[92:95], v[172:175], v[206:209], v[92:95]
	v_mfma_f32_16x16x32_bf16 v[80:83], v[164:167], v[214:217], v[80:83]
	v_mfma_f32_16x16x32_bf16 v[76:79], v[172:175], v[214:217], v[76:79]
	v_mfma_f32_16x16x32_bf16 v[128:131], v[168:171], v[184:187], v[128:131]
	v_mfma_f32_16x16x32_bf16 v[124:127], v[176:179], v[184:187], v[124:127]
	v_mfma_f32_16x16x32_bf16 v[112:115], v[168:171], v[192:195], v[112:115]
	v_mfma_f32_16x16x32_bf16 v[108:111], v[176:179], v[192:195], v[108:111]
	v_mfma_f32_16x16x32_bf16 v[96:99], v[168:171], v[210:213], v[96:99]
	v_mfma_f32_16x16x32_bf16 v[92:95], v[176:179], v[210:213], v[92:95]
	v_mfma_f32_16x16x32_bf16 v[80:83], v[168:171], v[218:221], v[80:83]
	v_mfma_f32_16x16x32_bf16 v[76:79], v[176:179], v[218:221], v[76:79]
	s_barrier
	s_add_i32 s41, s41, s35
	v_lshl_add_u64 v[234:235], s[20:21], 0, v[134:135]
	s_mov_b32 m0, s41
	ds_read_b128 v[180:183], v158 offset:16384
	ds_read_b128 v[184:187], v158 offset:17408
	ds_read_b128 v[188:191], v158 offset:18432
	ds_read_b128 v[192:195], v158 offset:19456
	ds_read_b128 v[206:209], v158 offset:20480
	ds_read_b128 v[210:213], v158 offset:21504
	ds_read_b128 v[214:217], v158 offset:22528
	ds_read_b128 v[218:221], v158 offset:23552
	global_load_lds_dwordx4 v[234:235], off
	s_add_i32 m0, s41, 0x2000
	s_add_u32 s42, s20, 0x40000
	v_lshl_add_u64 v[236:237], s[20:21], 0, v[138:139]
	s_addc_u32 s43, s21, 0
	s_add_i32 s41, s55, s35
	global_load_lds_dwordx4 v[236:237], off
	v_lshl_add_u64 v[238:239], s[42:43], 0, v[134:135]
	s_mov_b32 m0, s41
	v_lshl_add_u64 v[240:241], s[22:23], 0, v[136:137]
	global_load_lds_dwordx4 v[238:239], off
	v_lshl_add_u64 v[238:239], s[42:43], 0, v[138:139]
	s_add_i32 m0, s41, 0x2000
	s_nop 0
	global_load_lds_dwordx4 v[238:239], off
	v_lshl_add_u64 v[238:239], s[22:23], 0, v[132:133]
	s_mov_b32 m0, s36
	s_nop 0
	global_load_lds_dwordx4 v[238:239], off
	s_mov_b32 m0, s37
	s_nop 0
	global_load_lds_dwordx4 v[240:241], off
	s_waitcnt vmcnt(8)
	s_waitcnt lgkmcnt(0)
	s_barrier
	s_waitcnt lgkmcnt(0)
	v_mfma_f32_16x16x32_bf16 v[56:59], v[144:147], v[180:183], v[56:59]
	v_mfma_f32_16x16x32_bf16 v[52:55], v[152:155], v[180:183], v[52:55]
	v_mfma_f32_16x16x32_bf16 v[40:43], v[144:147], v[188:191], v[40:43]
	v_mfma_f32_16x16x32_bf16 v[36:39], v[152:155], v[188:191], v[36:39]
	v_mfma_f32_16x16x32_bf16 v[24:27], v[144:147], v[206:209], v[24:27]
	v_mfma_f32_16x16x32_bf16 v[20:23], v[152:155], v[206:209], v[20:23]
	v_mfma_f32_16x16x32_bf16 v[8:11], v[144:147], v[214:217], v[8:11]
	v_mfma_f32_16x16x32_bf16 v[4:7], v[152:155], v[214:217], v[4:7]
	v_mfma_f32_16x16x32_bf16 v[56:59], v[148:151], v[184:187], v[56:59]
	v_mfma_f32_16x16x32_bf16 v[52:55], v[160:163], v[184:187], v[52:55]
	v_mfma_f32_16x16x32_bf16 v[40:43], v[148:151], v[192:195], v[40:43]
	v_mfma_f32_16x16x32_bf16 v[36:39], v[160:163], v[192:195], v[36:39]
	v_mfma_f32_16x16x32_bf16 v[24:27], v[148:151], v[210:213], v[24:27]
	v_mfma_f32_16x16x32_bf16 v[20:23], v[160:163], v[210:213], v[20:23]
	v_mfma_f32_16x16x32_bf16 v[8:11], v[148:151], v[218:221], v[8:11]
	v_mfma_f32_16x16x32_bf16 v[4:7], v[160:163], v[218:221], v[4:7]
	v_mfma_f32_16x16x32_bf16 v[64:67], v[164:167], v[180:183], v[64:67]
	v_mfma_f32_16x16x32_bf16 v[60:63], v[172:175], v[180:183], v[60:63]
	v_mfma_f32_16x16x32_bf16 v[48:51], v[164:167], v[188:191], v[48:51]
	v_mfma_f32_16x16x32_bf16 v[44:47], v[172:175], v[188:191], v[44:47]
	v_mfma_f32_16x16x32_bf16 v[32:35], v[164:167], v[206:209], v[32:35]
	v_mfma_f32_16x16x32_bf16 v[28:31], v[172:175], v[206:209], v[28:31]
	v_mfma_f32_16x16x32_bf16 v[16:19], v[164:167], v[214:217], v[16:19]
	v_mfma_f32_16x16x32_bf16 v[12:15], v[172:175], v[214:217], v[12:15]
	v_mfma_f32_16x16x32_bf16 v[64:67], v[168:171], v[184:187], v[64:67]
	v_mfma_f32_16x16x32_bf16 v[60:63], v[176:179], v[184:187], v[60:63]
	v_mfma_f32_16x16x32_bf16 v[48:51], v[168:171], v[192:195], v[48:51]
	v_mfma_f32_16x16x32_bf16 v[44:47], v[176:179], v[192:195], v[44:47]
	v_mfma_f32_16x16x32_bf16 v[32:35], v[168:171], v[210:213], v[32:35]
	v_mfma_f32_16x16x32_bf16 v[28:31], v[176:179], v[210:213], v[28:31]
	v_mfma_f32_16x16x32_bf16 v[16:19], v[168:171], v[218:221], v[16:19]
	v_mfma_f32_16x16x32_bf16 v[12:15], v[176:179], v[218:221], v[12:15]
	s_barrier
	s_add_i32 s41, 0, 0x18000
	v_add_u32_e32 v2, s41, v157
	s_add_i32 s42, 0, 0x1c000
	ds_read_b128 v[144:147], v2
	ds_read_b128 v[148:151], v2 offset:1024
	ds_read_b128 v[152:155], v2 offset:2048
	ds_read_b128 v[160:163], v2 offset:3072
	v_add_u32_e32 v2, s42, v157
	ds_read_b128 v[164:167], v2
	ds_read_b128 v[168:171], v2 offset:1024
	ds_read_b128 v[172:175], v2 offset:2048
	ds_read_b128 v[176:179], v2 offset:3072
	s_add_u32 s22, s22, 0x40000
	s_addc_u32 s23, s23, 0
	s_mov_b32 m0, s64
	v_lshl_add_u64 v[242:243], s[22:23], 0, v[132:133]
	ds_read_b128 v[180:183], v158 offset:32768
	ds_read_b128 v[184:187], v158 offset:33792
	ds_read_b128 v[188:191], v158 offset:34816
	ds_read_b128 v[192:195], v158 offset:35840
	ds_read_b128 v[206:209], v158 offset:36864
	ds_read_b128 v[210:213], v158 offset:37888
	ds_read_b128 v[214:217], v158 offset:38912
	ds_read_b128 v[218:221], v158 offset:39936
	global_load_lds_dwordx4 v[242:243], off
	v_lshl_add_u64 v[242:243], s[22:23], 0, v[136:137]
	s_mov_b32 m0, s65
	s_nop 0
	global_load_lds_dwordx4 v[242:243], off
	s_waitcnt vmcnt(8)
	s_waitcnt lgkmcnt(0)
	s_barrier
	s_waitcnt lgkmcnt(0)
	v_mfma_f32_16x16x32_bf16 v[120:123], v[144:147], v[180:183], v[120:123]
	v_mfma_f32_16x16x32_bf16 v[116:119], v[152:155], v[180:183], v[116:119]
	v_mfma_f32_16x16x32_bf16 v[104:107], v[144:147], v[188:191], v[104:107]
	v_mfma_f32_16x16x32_bf16 v[100:103], v[152:155], v[188:191], v[100:103]
	v_mfma_f32_16x16x32_bf16 v[88:91], v[144:147], v[206:209], v[88:91]
	v_mfma_f32_16x16x32_bf16 v[84:87], v[152:155], v[206:209], v[84:87]
	v_mfma_f32_16x16x32_bf16 v[72:75], v[144:147], v[214:217], v[72:75]
	v_mfma_f32_16x16x32_bf16 v[68:71], v[152:155], v[214:217], v[68:71]
	v_mfma_f32_16x16x32_bf16 v[120:123], v[148:151], v[184:187], v[120:123]
	v_mfma_f32_16x16x32_bf16 v[116:119], v[160:163], v[184:187], v[116:119]
	v_mfma_f32_16x16x32_bf16 v[104:107], v[148:151], v[192:195], v[104:107]
	v_mfma_f32_16x16x32_bf16 v[100:103], v[160:163], v[192:195], v[100:103]
	v_mfma_f32_16x16x32_bf16 v[88:91], v[148:151], v[210:213], v[88:91]
	v_mfma_f32_16x16x32_bf16 v[84:87], v[160:163], v[210:213], v[84:87]
	v_mfma_f32_16x16x32_bf16 v[72:75], v[148:151], v[218:221], v[72:75]
	v_mfma_f32_16x16x32_bf16 v[68:71], v[160:163], v[218:221], v[68:71]
	v_mfma_f32_16x16x32_bf16 v[128:131], v[164:167], v[180:183], v[128:131]
	v_mfma_f32_16x16x32_bf16 v[124:127], v[172:175], v[180:183], v[124:127]
	v_mfma_f32_16x16x32_bf16 v[112:115], v[164:167], v[188:191], v[112:115]
	v_mfma_f32_16x16x32_bf16 v[108:111], v[172:175], v[188:191], v[108:111]
	v_mfma_f32_16x16x32_bf16 v[96:99], v[164:167], v[206:209], v[96:99]
	v_mfma_f32_16x16x32_bf16 v[92:95], v[172:175], v[206:209], v[92:95]
	v_mfma_f32_16x16x32_bf16 v[80:83], v[164:167], v[214:217], v[80:83]
	v_mfma_f32_16x16x32_bf16 v[76:79], v[172:175], v[214:217], v[76:79]
	v_mfma_f32_16x16x32_bf16 v[128:131], v[168:171], v[184:187], v[128:131]
	v_mfma_f32_16x16x32_bf16 v[124:127], v[176:179], v[184:187], v[124:127]
	v_mfma_f32_16x16x32_bf16 v[112:115], v[168:171], v[192:195], v[112:115]
	v_mfma_f32_16x16x32_bf16 v[108:111], v[176:179], v[192:195], v[108:111]
	v_mfma_f32_16x16x32_bf16 v[96:99], v[168:171], v[210:213], v[96:99]
	v_mfma_f32_16x16x32_bf16 v[92:95], v[176:179], v[210:213], v[92:95]
	v_mfma_f32_16x16x32_bf16 v[80:83], v[168:171], v[218:221], v[80:83]
	v_mfma_f32_16x16x32_bf16 v[76:79], v[176:179], v[218:221], v[76:79]
	s_barrier
	s_add_i32 s22, s41, s35
	v_lshl_add_u64 v[234:235], v[234:235], 0, s[96:97]
	s_mov_b32 m0, s22
	ds_read_b128 v[180:183], v158 offset:49152
	ds_read_b128 v[184:187], v158 offset:50176
	ds_read_b128 v[188:191], v158 offset:51200
	ds_read_b128 v[192:195], v158 offset:52224
	ds_read_b128 v[206:209], v158 offset:53248
	ds_read_b128 v[210:213], v158 offset:54272
	ds_read_b128 v[214:217], v158 offset:55296
	ds_read_b128 v[218:221], v158 offset:56320
	global_load_lds_dwordx4 v[234:235], off
	s_add_i32 m0, s22, 0x2000
	s_add_u32 s20, s20, 0x40080
	v_lshl_add_u64 v[234:235], v[236:237], 0, s[96:97]
	s_addc_u32 s21, s21, 0
	s_add_i32 s22, s42, s35
	global_load_lds_dwordx4 v[234:235], off
	v_lshl_add_u64 v[234:235], s[20:21], 0, v[134:135]
	s_mov_b32 m0, s22
	s_nop 0
	global_load_lds_dwordx4 v[234:235], off
	v_lshl_add_u64 v[234:235], s[20:21], 0, v[138:139]
	s_add_i32 m0, s22, 0x2000
	s_nop 0
	global_load_lds_dwordx4 v[234:235], off
	v_lshl_add_u64 v[234:235], v[238:239], 0, s[96:97]
	s_mov_b32 m0, s67
	s_nop 0
	global_load_lds_dwordx4 v[234:235], off
	v_lshl_add_u64 v[234:235], v[240:241], 0, s[96:97]
	s_mov_b32 m0, s68
	s_nop 0
	global_load_lds_dwordx4 v[234:235], off
	s_waitcnt vmcnt(8)
	s_waitcnt lgkmcnt(0)
	s_barrier
	s_waitcnt lgkmcnt(0)
	v_mfma_f32_16x16x32_bf16 v[56:59], v[144:147], v[180:183], v[56:59]
	v_mfma_f32_16x16x32_bf16 v[52:55], v[152:155], v[180:183], v[52:55]
	v_mfma_f32_16x16x32_bf16 v[40:43], v[144:147], v[188:191], v[40:43]
	v_mfma_f32_16x16x32_bf16 v[36:39], v[152:155], v[188:191], v[36:39]
	v_mfma_f32_16x16x32_bf16 v[24:27], v[144:147], v[206:209], v[24:27]
	v_mfma_f32_16x16x32_bf16 v[20:23], v[152:155], v[206:209], v[20:23]
	v_mfma_f32_16x16x32_bf16 v[8:11], v[144:147], v[214:217], v[8:11]
	v_mfma_f32_16x16x32_bf16 v[4:7], v[152:155], v[214:217], v[4:7]
	v_mfma_f32_16x16x32_bf16 v[56:59], v[148:151], v[184:187], v[56:59]
	v_mfma_f32_16x16x32_bf16 v[52:55], v[160:163], v[184:187], v[52:55]
	v_mfma_f32_16x16x32_bf16 v[40:43], v[148:151], v[192:195], v[40:43]
	v_mfma_f32_16x16x32_bf16 v[36:39], v[160:163], v[192:195], v[36:39]
	v_mfma_f32_16x16x32_bf16 v[24:27], v[148:151], v[210:213], v[24:27]
	v_mfma_f32_16x16x32_bf16 v[20:23], v[160:163], v[210:213], v[20:23]
	v_mfma_f32_16x16x32_bf16 v[8:11], v[148:151], v[218:221], v[8:11]
	v_mfma_f32_16x16x32_bf16 v[4:7], v[160:163], v[218:221], v[4:7]
	v_mfma_f32_16x16x32_bf16 v[64:67], v[164:167], v[180:183], v[64:67]
	v_mfma_f32_16x16x32_bf16 v[60:63], v[172:175], v[180:183], v[60:63]
	v_mfma_f32_16x16x32_bf16 v[48:51], v[164:167], v[188:191], v[48:51]
	v_mfma_f32_16x16x32_bf16 v[44:47], v[172:175], v[188:191], v[44:47]
	v_mfma_f32_16x16x32_bf16 v[32:35], v[164:167], v[206:209], v[32:35]
	v_mfma_f32_16x16x32_bf16 v[28:31], v[172:175], v[206:209], v[28:31]
	v_mfma_f32_16x16x32_bf16 v[16:19], v[164:167], v[214:217], v[16:19]
	v_mfma_f32_16x16x32_bf16 v[12:15], v[172:175], v[214:217], v[12:15]
	v_mfma_f32_16x16x32_bf16 v[64:67], v[168:171], v[184:187], v[64:67]
	v_mfma_f32_16x16x32_bf16 v[60:63], v[176:179], v[184:187], v[60:63]
	v_mfma_f32_16x16x32_bf16 v[48:51], v[168:171], v[192:195], v[48:51]
	v_mfma_f32_16x16x32_bf16 v[44:47], v[176:179], v[192:195], v[44:47]
	v_mfma_f32_16x16x32_bf16 v[32:35], v[168:171], v[210:213], v[32:35]
	v_mfma_f32_16x16x32_bf16 v[28:31], v[176:179], v[210:213], v[28:31]
	v_mfma_f32_16x16x32_bf16 v[16:19], v[168:171], v[218:221], v[16:19]
	v_mfma_f32_16x16x32_bf16 v[12:15], v[176:179], v[218:221], v[12:15]
	s_barrier
	s_add_i32 s40, s40, 2
	s_add_u32 s18, s18, 0x100
	s_addc_u32 s19, s19, 0
	s_add_u32 s26, s26, 0x100
	s_addc_u32 s27, s27, 0
	s_cmp_gt_u32 s40, 13
	s_cbranch_scc0 .LBB0_752
	s_and_b64 vcc, exec, s[46:47]
	s_cbranch_vccz .LBB0_755
	s_barrier
